# LayerNorm / router wave reductions: ds_bpermute butterfly steps replaced by bit-identical DPP and permlane-swap steps (no LDS round trips)
# speedup vs baseline: 1.0051x; 1.0044x over previous
;     ...
;             for (int j = 0; j < 4; ++j) v[j] = ld4h(Ysrc + (size_t)m * DM + (lane + 64 * j) * 4);
;         } else {
;             const f32x4 rt = route[m]; const int s1 = slots[2 * m], s2 = slots[2 * m + 1];
;             const float mu1 = st[(size_t)m * 32 + 20], rs1 = st[(size_t)m * 32 + 21];
; #pragma unroll
;             for (int j = 0; j < 4; ++j) { const f32x4 yv1 = ld4h(Ysrc + (size_t)m * DM + (lane + 64 * j) * 4);
;                 const f32x4 xv = (yv1 - mu1) * rs1 * *((const f32x4*)g1 + lane + 64 * j) + *((const f32x4*)b1 + lane + 64 * j);
;                 const unsigned o1 = *((const unsigned*)((const unsigned char*)oslot + (size_t)s1 * DM) + lane + 64 * j), o2 = *((const unsigned*)((const unsigned char*)oslot + (size_t)s2 * DM) + lane + 64 * j);
;                 const unsigned p1 = *((const unsigned*)((const unsigned char*)oslot2 + (size_t)s1 * DM) + lane + 64 * j), p2 = *((const unsigned*)((const unsigned char*)oslot2 + (size_t)s2 * DM) + lane + 64 * j);
;                 const f32x2 a1l = __builtin_amdgcn_cvt_pk_f32_fp8((int)o1, false), a1h = __builtin_amdgcn_cvt_pk_f32_fp8((int)o1, true), b1l = __builtin_amdgcn_cvt_pk_f32_fp8((int)p1, false), b1h = __builtin_amdgcn_cvt_pk_f32_fp8((int)p1, true);
;                 const f32x2 a2l = __builtin_amdgcn_cvt_pk_f32_fp8((int)o2, false), a2h = __builtin_amdgcn_cvt_pk_f32_fp8((int)o2, true), b2l = __builtin_amdgcn_cvt_pk_f32_fp8((int)p2, false), b2h = __builtin_amdgcn_cvt_pk_f32_fp8((int)p2, true);
;                 const float g1s = rt[2] * (1.0f / O8), g2s = rt[3] * (1.0f / O8);
;                 f32x4 r;
;                 r[0] = xv[0] * DN_ALPHA + g1s * (a1l.x + b1l.x) + g2s * (a2l.x + b2l.x);
;                 r[1] = xv[1] * DN_ALPHA + g1s * (a1l.y + b1l.y) + g2s * (a2l.y + b2l.y);
;                 r[2] = xv[2] * DN_ALPHA + g1s * (a1h.x + b1h.x) + g2s * (a2h.x + b2h.x);
;                 r[3] = xv[3] * DN_ALPHA + g1s * (a1h.y + b1h.y) + g2s * (a2h.y + b2h.y);
;                 if constexpr (WRY) st4h((ystream_t*)Ysrc + (size_t)m * DM + (lane + 64 * j) * 4, r);
;                 v[j] = r; }
;         }
;         float s = 0.f;
; #pragma unroll
;         for (int j = 0; j < 4; ++j) s += (v[j][0] + v[j][1]) + (v[j][2] + v[j][3]);
;         const float mean = wave_sum(s) * (1.f / DM); float s2 = 0.f;
; #pragma unroll
.LBB0_1061:
	global_load_dwordx2 v[2:3], v[48:49], off offset:-1024
	global_load_dwordx2 v[8:9], v[48:49], off offset:-512
	global_load_dwordx2 v[20:21], v[48:49], off
	global_load_dwordx2 v[22:23], v[48:49], off offset:512
	s_mov_b32 s4, 0xba800000
	s_waitcnt vmcnt(0)
	v_cvt_f32_f16_sdwa v5, v3 dst_sel:DWORD dst_unused:UNUSED_PAD src0_sel:WORD_1
	v_cvt_f32_f16_sdwa v6, v2 dst_sel:DWORD dst_unused:UNUSED_PAD src0_sel:WORD_1
	v_cvt_f32_f16_e32 v4, v2
	v_cvt_f32_f16_e32 v7, v3
	v_cvt_f32_f16_sdwa v11, v9 dst_sel:DWORD dst_unused:UNUSED_PAD src0_sel:WORD_1
	v_cvt_f32_f16_sdwa v12, v8 dst_sel:DWORD dst_unused:UNUSED_PAD src0_sel:WORD_1
	v_cvt_f32_f16_e32 v10, v8
	v_cvt_f32_f16_e32 v13, v9
	v_cvt_f32_f16_sdwa v0, v21 dst_sel:DWORD dst_unused:UNUSED_PAD src0_sel:WORD_1
	v_cvt_f32_f16_sdwa v14, v20 dst_sel:DWORD dst_unused:UNUSED_PAD src0_sel:WORD_1
	v_cvt_f32_f16_e32 v52, v21
	v_cvt_f32_f16_e32 v16, v20
	v_cvt_f32_f16_sdwa v53, v22 dst_sel:DWORD dst_unused:UNUSED_PAD src0_sel:WORD_1
	v_pk_add_f32 v[4:5], v[6:7], v[4:5]
	v_cvt_f32_f16_sdwa v15, v23 dst_sel:DWORD dst_unused:UNUSED_PAD src0_sel:WORD_1
	v_cvt_f32_f16_e32 v17, v23
	v_cvt_f32_f16_e32 v19, v22
	v_add_f32_e32 v4, v4, v5
	v_add_f32_e32 v18, 0, v4
	v_pk_add_f32 v[4:5], v[12:13], v[10:11]
	v_add_f32_e32 v16, v16, v14
	v_pk_add_f32 v[4:5], v[4:5], v[4:5] op_sel:[0,1] op_sel_hi:[1,0]
	v_add_f32_e32 v14, v52, v0
	v_mov_b32_e32 v5, v53
	v_pk_add_f32 v[4:5], v[18:19], v[4:5]
	v_pk_add_f32 v[6:7], v[16:17], v[14:15]
	s_nop 0
	v_pk_add_f32 v[4:5], v[4:5], v[6:7]
	s_nop 0
	v_add_f32_e32 v0, v4, v5
	s_nop 1
	v_mov_b32_dpp v4, v0 quad_perm:[1,0,3,2] row_mask:0xf bank_mask:0xf
	s_nop 0
	s_waitcnt lgkmcnt(0)
	v_add_f32_e32 v0, v0, v4
	s_nop 1
	v_mov_b32_dpp v4, v0 quad_perm:[2,3,0,1] row_mask:0xf bank_mask:0xf
	s_nop 0
	s_waitcnt lgkmcnt(0)
	v_add_f32_e32 v0, v0, v4
	s_nop 1
	v_mov_b32_dpp v4, v0 row_shl:4 row_mask:0xf bank_mask:0x5
	v_mov_b32_dpp v4, v0 row_shr:4 row_mask:0xf bank_mask:0xa
	s_nop 0
	s_waitcnt lgkmcnt(0)
	v_add_f32_e32 v0, v0, v4
	s_nop 1
	v_mov_b32_dpp v4, v0 row_ror:8 row_mask:0xf bank_mask:0xf
	s_nop 0
	s_waitcnt lgkmcnt(0)
	v_add_f32_e32 v0, v0, v4
	s_nop 1
	v_mov_b32_e32 v4, v0
	v_mov_b32_e32 v79, v0
	s_nop 1
	v_permlane16_swap_b32_e32 v4, v79
	s_nop 1
	v_mov_b32_dpp v4, v79 quad_perm:[0,1,2,3] row_mask:0x5 bank_mask:0xf
	s_nop 0
	s_waitcnt lgkmcnt(0)
	v_add_f32_e32 v0, v0, v4
	s_nop 1
	v_mov_b32_e32 v4, v0
	v_mov_b32_e32 v79, v0
	s_nop 1
	v_permlane32_swap_b32_e32 v4, v79
	s_nop 1
	v_mov_b32_dpp v4, v79 quad_perm:[0,1,2,3] row_mask:0x3 bank_mask:0xf
	s_nop 0
	s_waitcnt lgkmcnt(0)
	v_add_f32_e32 v18, v0, v4
	v_fma_mix_f32 v15, v18, s4, v2 op_sel:[0,0,1] op_sel_hi:[0,0,1]
	v_fma_mix_f32 v14, v18, s4, v2 op_sel_hi:[0,0,1]
	v_fma_mix_f32 v17, v18, s4, v3 op_sel:[0,0,1] op_sel_hi:[0,0,1]
	v_fma_mix_f32 v16, v18, s4, v3 op_sel_hi:[0,0,1]
	v_pk_mul_f32 v[2:3], v[16:17], v[16:17]
	v_pk_mul_f32 v[4:5], v[14:15], v[14:15]
	v_fma_mix_f32 v11, v18, s4, v8 op_sel:[0,0,1] op_sel_hi:[0,0,1]
	v_pk_mov_b32 v[6:7], v[4:5], v[2:3] op_sel:[1,0]
	v_mov_b32_e32 v5, v3
	v_pk_add_f32 v[2:3], v[6:7], v[4:5]
	v_fma_mix_f32 v10, v18, s4, v8 op_sel_hi:[0,0,1]
	v_fma_mix_f32 v13, v18, s4, v9 op_sel:[0,0,1] op_sel_hi:[0,0,1]
	v_fma_mix_f32 v12, v18, s4, v9 op_sel_hi:[0,0,1]
	v_pk_add_f32 v[52:53], v[2:3], v[2:3] op_sel_hi:[0,1]
	v_pk_mul_f32 v[2:3], v[12:13], v[12:13]
	v_pk_mul_f32 v[4:5], v[10:11], v[10:11]
	v_fma_mix_f32 v8, v18, s4, v21 op_sel_hi:[0,0,1]
	v_pk_mov_b32 v[6:7], v[4:5], v[2:3] op_sel:[1,0]
	v_mov_b32_e32 v5, v3
	v_pk_add_f32 v[2:3], v[6:7], v[4:5]
	v_fma_mix_f32 v6, v18, s4, v20 op_sel_hi:[0,0,1]
	v_fma_mix_f32 v7, v18, s4, v20 op_sel:[0,0,1] op_sel_hi:[0,0,1]
	v_mul_f32_e32 v0, v6, v6
	v_fma_mix_f32 v9, v18, s4, v21 op_sel:[0,0,1] op_sel_hi:[0,0,1]
	v_pk_fma_f32 v[20:21], v[6:7], v[6:7], v[0:1] op_sel_hi:[1,1,0]
	v_mul_f32_e32 v0, v8, v8
	v_pk_add_f32 v[54:55], v[2:3], v[2:3] op_sel_hi:[0,1]
	v_pk_fma_f32 v[56:57], v[8:9], v[8:9], v[0:1] op_sel_hi:[1,1,0]
	v_fma_mix_f32 v3, v18, s4, v23 op_sel:[0,0,1] op_sel_hi:[0,0,1]
	v_fma_mix_f32 v2, v18, s4, v23 op_sel_hi:[0,0,1]
	v_fma_mix_f32 v5, v18, s4, v22 op_sel:[0,0,1] op_sel_hi:[0,0,1]
	v_fma_mix_f32 v4, v18, s4, v22 op_sel_hi:[0,0,1]
	v_mul_f32_e32 v20, v4, v4
	v_mul_f32_e32 v56, v5, v5
	v_mul_f32_e32 v52, v2, v2
	v_mul_f32_e32 v54, v3, v3
	v_pk_add_f32 v[20:21], v[20:21], v[56:57]
	v_pk_add_f32 v[22:23], v[52:53], v[54:55]
	s_nop 0
	v_pk_add_f32 v[20:21], v[20:21], v[22:23]
	s_nop 0
	v_add_f32_e32 v0, v20, v21
	global_load_dwordx4 v[20:23], v[26:27], off
	global_load_dwordx4 v[52:55], v[28:29], off
	s_nop 1
	v_mov_b32_dpp v19, v0 quad_perm:[1,0,3,2] row_mask:0xf bank_mask:0xf
	s_nop 0
	s_waitcnt lgkmcnt(0)
	v_add_f32_e32 v0, v0, v19
	s_nop 1
	v_mov_b32_dpp v19, v0 quad_perm:[2,3,0,1] row_mask:0xf bank_mask:0xf
	s_nop 0
	s_waitcnt lgkmcnt(0)
	v_add_f32_e32 v0, v0, v19
	s_nop 1
	v_mov_b32_dpp v19, v0 row_shl:4 row_mask:0xf bank_mask:0x5
	v_mov_b32_dpp v19, v0 row_shr:4 row_mask:0xf bank_mask:0xa
	s_nop 0
	s_waitcnt lgkmcnt(0)
	v_add_f32_e32 v0, v0, v19
	s_nop 1
	v_mov_b32_dpp v19, v0 row_ror:8 row_mask:0xf bank_mask:0xf
	s_nop 0
	s_waitcnt lgkmcnt(0)
	v_add_f32_e32 v0, v0, v19
	s_nop 1
	v_mov_b32_e32 v19, v0
	v_mov_b32_e32 v79, v0
	s_nop 1
	v_permlane16_swap_b32_e32 v19, v79
	s_nop 1
	v_mov_b32_dpp v19, v79 quad_perm:[0,1,2,3] row_mask:0x5 bank_mask:0xf
	s_nop 0
	s_waitcnt lgkmcnt(0)
	v_add_f32_e32 v0, v0, v19
	s_nop 1
	v_mov_b32_e32 v19, v0
	v_mov_b32_e32 v79, v0
	s_nop 1
	v_permlane32_swap_b32_e32 v19, v79
	s_nop 1
	v_mov_b32_dpp v19, v79 quad_perm:[0,1,2,3] row_mask:0x3 bank_mask:0xf
	s_nop 0
	s_waitcnt lgkmcnt(0)
; __device__ __forceinline__ unsigned cvt_pk_bf16(float lo, float hi) { unsigned r; asm volatile("v_cvt_pk_bf16_f32 %0, %1, %2" : "=v"(r) : "v"(lo), "v"(hi)); return r; }
; __device__ __forceinline__ unsigned cvt4_fp8(float a, float b, float c, float d) { unsigned w = __builtin_amdgcn_cvt_pk_fp8_f32(a, b, 0u, false); return (unsigned)__builtin_amdgcn_cvt_pk_fp8_f32(c, d, (int)w, true); }
;     ...
;         const float rstd = __builtin_amdgcn_rsqf(wave_sum(s2) * (1.f / DM) + 1e-5f);
; #pragma unroll
;         for (int j = 0; j < 4; ++j) { const f32x4 gv = *((const f32x4*)g + lane + 64 * j), bv = *((const f32x4*)b + lane + 64 * j);
;             v[j] = v[j] * rstd * gv + bv;
;             if constexpr (!NOX) *((f32x4*)(Xout + (size_t)m * DM) + lane + 64 * j) = v[j];
;             if constexpr (OUT8) { *((unsigned*)((unsigned char*)XB + (size_t)m * DM) + lane + 64 * j) = cvt4_fp8(v[j][0], v[j][1], v[j][2], v[j][3]); }
;             else if (XB) { u32x2 w; w.x = cvt_pk_bf16(v[j][0], v[j][1]); w.y = cvt_pk_bf16(v[j][2], v[j][3]); *((u32x2*)(XB + (size_t)m * DM) + lane + 64 * j) = w; } }
;         if constexpr (NOX) { if (lane == 0) { st[(size_t)m * 32 + stslot] = mean; st[(size_t)m * 32 + stslot + 1] = rstd; } }
;         if constexpr (ROUTE) {
;             float lg[8];
; #pragma unroll
;             for (int e = 0; e < 8; ++e) lg[e] = 0.f;
; #pragma unroll
;             for (int j = 0; j < 4; ++j)
; #pragma unroll
;                 for (int q = 0; q < 4; ++q) { const int k = (lane + 64 * j) * 4 + q; const f32x4 r0 = *(const f32x4*)(router + (size_t)k * 8), r1 = *(const f32x4*)(router + (size_t)k * 8 + 4); const float xv = v[j][q];
;                     lg[0] += xv * r0[0]; lg[1] += xv * r0[1]; lg[2] += xv * r0[2]; lg[3] += xv * r0[3]; lg[4] += xv * r1[0]; lg[5] += xv * r1[1]; lg[6] += xv * r1[2]; lg[7] += xv * r1[3]; }
	v_add_f32_e32 v0, v0, v19
	v_fmamk_f32 v0, v0, 0x3a800000, v199
	v_rsq_f32_e32 v0, v0
	s_nop 0
	v_pk_mul_f32 v[14:15], v[14:15], v[0:1] op_sel_hi:[1,0]
	v_pk_mul_f32 v[16:17], v[16:17], v[0:1] op_sel_hi:[1,0]
	v_pk_mul_f32 v[10:11], v[10:11], v[0:1] op_sel_hi:[1,0]
	v_pk_mul_f32 v[12:13], v[12:13], v[0:1] op_sel_hi:[1,0]
	v_pk_mul_f32 v[6:7], v[6:7], v[0:1] op_sel_hi:[1,0]
	v_pk_mul_f32 v[8:9], v[8:9], v[0:1] op_sel_hi:[1,0]
	v_pk_mul_f32 v[4:5], v[4:5], v[0:1] op_sel_hi:[1,0]
	v_pk_mul_f32 v[2:3], v[2:3], v[0:1] op_sel_hi:[1,0]
	s_waitcnt vmcnt(0)
	v_pk_fma_f32 v[56:57], v[20:21], v[14:15], v[52:53]
	v_mov_b32_e32 v14, v1
	v_cvt_pk_fp8_f32 v14, v56, v57
	v_pk_fma_f32 v[54:55], v[22:23], v[16:17], v[54:55]
	s_nop 0
	v_cvt_pk_fp8_f32 v14, v54, v55 op_sel:[0,0,1]
	global_store_dword v[50:51], v14, off offset:-512
	global_load_dwordx4 v[14:17], v[26:27], off offset:1024
	s_nop 0
	global_load_dwordx4 v[20:23], v[28:29], off offset:1024
	s_waitcnt vmcnt(0)
	v_pk_fma_f32 v[64:65], v[14:15], v[10:11], v[20:21]
	v_mov_b32_e32 v10, v1
	v_cvt_pk_fp8_f32 v10, v64, v65
	v_pk_fma_f32 v[62:63], v[16:17], v[12:13], v[22:23]
	s_nop 0
	v_cvt_pk_fp8_f32 v10, v62, v63 op_sel:[0,0,1]
	global_store_dword v[50:51], v10, off offset:-256
	global_load_dwordx4 v[10:13], v[26:27], off offset:2048
	s_nop 0
	global_load_dwordx4 v[14:17], v[28:29], off offset:2048
	s_waitcnt vmcnt(0)
	v_pk_fma_f32 v[66:67], v[10:11], v[6:7], v[14:15]
	v_mov_b32_e32 v6, v1
	v_cvt_pk_fp8_f32 v6, v66, v67
	v_pk_fma_f32 v[60:61], v[12:13], v[8:9], v[16:17]
	s_nop 0
	v_cvt_pk_fp8_f32 v6, v60, v61 op_sel:[0,0,1]
	global_store_dword v[50:51], v6, off
	global_load_dwordx4 v[6:9], v[26:27], off offset:3072
	s_nop 0
	global_load_dwordx4 v[10:13], v[28:29], off offset:3072
	s_waitcnt vmcnt(0)
	v_pk_fma_f32 v[52:53], v[8:9], v[2:3], v[12:13]
	v_pk_fma_f32 v[58:59], v[6:7], v[4:5], v[10:11]
	v_mov_b32_e32 v2, v1
	v_cvt_pk_fp8_f32 v2, v58, v59
	v_cvt_pk_fp8_f32 v2, v52, v53 op_sel:[0,0,1]
	global_store_dword v[50:51], v2, off offset:256
	s_and_saveexec_b64 s[4:5], s[42:43]
	s_cbranch_execz .LBB0_1063
	v_mul_f32_e32 v2, 0x3a800000, v18
	v_mov_b32_e32 v3, v0
	global_store_dwordx2 v1, v[2:3], s[24:25]
.LBB0_1063:
	s_or_b64 exec, exec, s[4:5]
	global_load_dwordx4 v[2:5], v[32:33], off offset:48
	global_load_dwordx4 v[6:9], v[32:33], off offset:32
	global_load_dwordx4 v[14:17], v[32:33], off offset:16
	global_load_dwordx4 v[10:13], v[32:33], off
	s_mov_b32 s8, 0xff800000
	s_waitcnt vmcnt(1)
	v_fma_f32 v76, v56, v14, 0
	v_fma_f32 v75, v56, v15, 0
	v_fma_f32 v74, v56, v16, 0
	v_fma_f32 v0, v56, v17, 0
	s_waitcnt vmcnt(0)
	v_fma_f32 v78, v56, v12, 0
	v_fma_f32 v77, v56, v13, 0
	v_fmac_f32_e32 v76, v57, v2
	v_fmac_f32_e32 v75, v57, v3
	v_fmac_f32_e32 v74, v57, v4
	v_fmac_f32_e32 v0, v57, v5
	global_load_dwordx4 v[12:15], v[34:35], off offset:48
	global_load_dwordx4 v[2:5], v[34:35], off offset:32
	global_load_dwordx4 v[20:23], v[34:35], off offset:16
	global_load_dwordx4 v[16:19], v[34:35], off
	v_fmac_f32_e32 v78, v57, v8
	v_fmac_f32_e32 v77, v57, v9
	s_waitcnt vmcnt(1)
	v_fmac_f32_e32 v76, v54, v20
	v_fmac_f32_e32 v75, v54, v21
	v_fmac_f32_e32 v74, v54, v22
	v_fmac_f32_e32 v0, v54, v23
	s_waitcnt vmcnt(0)
	v_fmac_f32_e32 v78, v54, v18
	v_fmac_f32_e32 v77, v54, v19
	v_fmac_f32_e32 v76, v55, v12
	v_fmac_f32_e32 v75, v55, v13
	v_fmac_f32_e32 v74, v55, v14
	v_fmac_f32_e32 v0, v55, v15
	global_load_dwordx4 v[80:83], v[36:37], off offset:48
	global_load_dwordx4 v[12:15], v[36:37], off offset:32
	global_load_dwordx4 v[84:87], v[36:37], off offset:16
	global_load_dwordx4 v[18:21], v[36:37], off
	v_fmac_f32_e32 v78, v55, v4
	v_fmac_f32_e32 v77, v55, v5
	v_pk_fma_f32 v[4:5], v[56:57], v[10:11], 0 op_sel_hi:[0,1,0]
	v_pk_fma_f32 v[4:5], v[56:57], v[6:7], v[4:5] op_sel:[1,0,0]
	v_mov_b32_e32 v6, v55
	v_pk_fma_f32 v[4:5], v[54:55], v[16:17], v[4:5] op_sel_hi:[0,1,1]
	v_pk_fma_f32 v[2:3], v[6:7], v[2:3], v[4:5] op_sel_hi:[0,1,1]
	v_mov_b32_e32 v4, v63
	s_waitcnt vmcnt(1)
	v_fmac_f32_e32 v76, v64, v84
	v_fmac_f32_e32 v75, v64, v85
	v_fmac_f32_e32 v74, v64, v86
	v_fmac_f32_e32 v0, v64, v87
	s_waitcnt vmcnt(0)
	v_fmac_f32_e32 v78, v64, v20
	v_fmac_f32_e32 v77, v64, v21
	v_fmac_f32_e32 v76, v65, v80
	v_fmac_f32_e32 v75, v65, v81
	v_fmac_f32_e32 v74, v65, v82
	v_fmac_f32_e32 v0, v65, v83
	global_load_dwordx4 v[80:83], v[38:39], off offset:48
	global_load_dwordx4 v[20:23], v[38:39], off offset:32
	global_load_dwordx4 v[84:87], v[38:39], off offset:16
	global_load_dwordx4 v[88:91], v[38:39], off
	v_fmac_f32_e32 v78, v65, v14
	v_fmac_f32_e32 v77, v65, v15
	v_pk_fma_f32 v[2:3], v[64:65], v[18:19], v[2:3] op_sel_hi:[0,1,1]
	v_pk_fma_f32 v[2:3], v[64:65], v[12:13], v[2:3] op_sel:[1,0,0]
	s_waitcnt vmcnt(1)
	v_fmac_f32_e32 v76, v62, v84
	v_fmac_f32_e32 v75, v62, v85
	v_fmac_f32_e32 v74, v62, v86
	v_fmac_f32_e32 v0, v62, v87
	s_waitcnt vmcnt(0)
	v_fmac_f32_e32 v78, v62, v90
	v_fmac_f32_e32 v77, v62, v91
	v_fmac_f32_e32 v76, v63, v80
	v_fmac_f32_e32 v75, v63, v81
	v_fmac_f32_e32 v74, v63, v82
	v_fmac_f32_e32 v0, v63, v83
	global_load_dwordx4 v[80:83], v[40:41], off offset:48
	global_load_dwordx4 v[84:87], v[40:41], off offset:32
	global_load_dwordx4 v[90:93], v[40:41], off offset:16
	global_load_dwordx4 v[94:97], v[40:41], off
	v_pk_fma_f32 v[2:3], v[62:63], v[88:89], v[2:3] op_sel_hi:[0,1,1]
	v_pk_fma_f32 v[2:3], v[4:5], v[20:21], v[2:3] op_sel_hi:[0,1,1]
	v_fmac_f32_e32 v78, v63, v22
	v_fmac_f32_e32 v77, v63, v23
	s_waitcnt vmcnt(1)
	v_fmac_f32_e32 v76, v66, v90
	s_waitcnt vmcnt(0)
;     ...
;             for (int j = 0; j < 4; ++j)
; #pragma unroll
;                 for (int q = 0; q < 4; ++q) { const int k = (lane + 64 * j) * 4 + q; const f32x4 r0 = *(const f32x4*)(router + (size_t)k * 8), r1 = *(const f32x4*)(router + (size_t)k * 8 + 4); const float xv = v[j][q];
;                     lg[0] += xv * r0[0]; lg[1] += xv * r0[1]; lg[2] += xv * r0[2]; lg[3] += xv * r0[3]; lg[4] += xv * r1[0]; lg[5] += xv * r1[1]; lg[6] += xv * r1[2]; lg[7] += xv * r1[3]; }
; #pragma unroll
;             for (int e = 0; e < 8; ++e) lg[e] = wave_sum(lg[e]);
	v_pk_fma_f32 v[2:3], v[66:67], v[94:95], v[2:3] op_sel_hi:[0,1,1]
	v_pk_fma_f32 v[18:19], v[66:67], v[84:85], v[2:3] op_sel:[1,0,0]
	global_load_dwordx4 v[2:5], v[42:43], off offset:16
	global_load_dwordx4 v[6:9], v[42:43], off offset:48
	global_load_dwordx4 v[10:13], v[42:43], off
	global_load_dwordx4 v[14:17], v[42:43], off offset:32
	v_fmac_f32_e32 v78, v66, v96
	v_fmac_f32_e32 v78, v67, v86
	v_fmac_f32_e32 v77, v66, v97
	v_fmac_f32_e32 v77, v67, v87
	v_fmac_f32_e32 v76, v67, v80
	v_fmac_f32_e32 v75, v66, v91
	v_fmac_f32_e32 v75, v67, v81
	v_fmac_f32_e32 v74, v66, v92
	v_fmac_f32_e32 v0, v66, v93
	v_fmac_f32_e32 v74, v67, v82
	v_fmac_f32_e32 v0, v67, v83
	s_waitcnt vmcnt(1)
	v_mov_b32_e32 v20, v10
	s_waitcnt vmcnt(0)
	v_mov_b32_e32 v21, v14
	v_mov_b32_e32 v14, v11
	v_mov_b32_e32 v10, v12
	v_mov_b32_e32 v11, v16
	v_pk_mul_f32 v[10:11], v[60:61], v[10:11]
	v_mov_b32_e32 v16, v13
	v_add_f32_e32 v10, v78, v10
	v_add_f32_e32 v62, v10, v11
	v_pk_mul_f32 v[10:11], v[60:61], v[16:17]
	v_pk_mul_f32 v[22:23], v[60:61], v[14:15]
	v_add_f32_e32 v10, v77, v10
	v_add_f32_e32 v64, v10, v11
	v_mov_b32_e32 v10, v2
	v_mov_b32_e32 v11, v6
	v_pk_mul_f32 v[10:11], v[60:61], v[10:11]
	v_mov_b32_e32 v6, v3
	v_add_f32_e32 v2, v76, v10
	v_add_f32_e32 v65, v2, v11
	v_pk_mul_f32 v[2:3], v[60:61], v[6:7]
	v_pk_mul_f32 v[20:21], v[60:61], v[20:21]
	v_add_f32_e32 v2, v75, v2
	v_add_f32_e32 v66, v2, v3
	v_mov_b32_e32 v2, v4
	v_mov_b32_e32 v3, v8
	v_pk_mul_f32 v[2:3], v[60:61], v[2:3]
	v_mov_b32_e32 v8, v5
	v_add_f32_e32 v2, v74, v2
	v_add_f32_e32 v67, v2, v3
	v_pk_mul_f32 v[2:3], v[60:61], v[8:9]
	s_nop 0
	v_add_f32_e32 v0, v0, v2
	v_add_f32_e32 v74, v0, v3
	global_load_dwordx4 v[2:5], v[44:45], off offset:16
	global_load_dwordx4 v[6:9], v[44:45], off offset:48
	global_load_dwordx4 v[10:13], v[44:45], off
	global_load_dwordx4 v[14:17], v[44:45], off offset:32
	s_waitcnt vmcnt(1)
	v_mov_b32_e32 v54, v10
	s_waitcnt vmcnt(0)
	v_mov_b32_e32 v55, v14
	v_mov_b32_e32 v14, v11
	v_mov_b32_e32 v10, v12
	v_mov_b32_e32 v11, v16
	v_pk_mul_f32 v[10:11], v[58:59], v[10:11]
	v_mov_b32_e32 v16, v13
	v_add_f32_e32 v0, v62, v10
	v_add_f32_e32 v63, v0, v11
	v_pk_mul_f32 v[10:11], v[58:59], v[16:17]
	v_pk_mul_f32 v[54:55], v[58:59], v[54:55]
	v_add_f32_e32 v0, v64, v10
	v_add_f32_e32 v62, v0, v11
	v_mov_b32_e32 v11, v6
	v_mov_b32_e32 v6, v3
	v_mov_b32_e32 v10, v2
	v_pk_mul_f32 v[2:3], v[58:59], v[6:7]
	v_pk_mul_f32 v[10:11], v[58:59], v[10:11]
	v_add_f32_e32 v2, v66, v2
	v_add_f32_e32 v60, v2, v3
	v_mov_b32_e32 v2, v4
	v_mov_b32_e32 v3, v8
	v_pk_mul_f32 v[2:3], v[58:59], v[2:3]
	v_mov_b32_e32 v8, v5
	v_add_f32_e32 v2, v67, v2
	v_add_f32_e32 v61, v2, v3
	v_pk_mul_f32 v[2:3], v[58:59], v[8:9]
	v_add_f32_e32 v0, v65, v10
	v_add_f32_e32 v2, v74, v2
	v_pk_mul_f32 v[56:57], v[58:59], v[14:15]
	v_add_f32_e32 v0, v0, v11
	v_add_f32_e32 v58, v2, v3
	global_load_dwordx4 v[2:5], v[46:47], off offset:16
	global_load_dwordx4 v[6:9], v[46:47], off offset:48
	global_load_dwordx4 v[10:13], v[46:47], off
	global_load_dwordx4 v[14:17], v[46:47], off offset:32
	s_waitcnt vmcnt(1)
	v_mov_b32_e32 v64, v10
	s_waitcnt vmcnt(0)
	v_mov_b32_e32 v65, v14
	v_mov_b32_e32 v14, v11
	v_pk_mul_f32 v[10:11], v[52:53], v[14:15]
	v_mov_b32_e32 v14, v12
	v_mov_b32_e32 v15, v16
	v_pk_mul_f32 v[14:15], v[52:53], v[14:15]
	v_mov_b32_e32 v16, v13
	v_add_f32_e32 v12, v63, v14
	v_add_f32_e32 v14, v12, v15
	v_pk_mul_f32 v[12:13], v[52:53], v[16:17]
	v_pk_mul_f32 v[64:65], v[52:53], v[64:65]
	v_add_f32_e32 v12, v62, v12
	v_add_f32_e32 v15, v12, v13
	v_mov_b32_e32 v12, v2
	v_mov_b32_e32 v13, v6
	v_pk_mul_f32 v[12:13], v[52:53], v[12:13]
	v_mov_b32_e32 v6, v3
	v_add_f32_e32 v0, v0, v12
	v_pk_mul_f32 v[2:3], v[52:53], v[6:7]
	v_add_f32_e32 v12, v0, v13
	v_add_f32_e32 v0, v60, v2
	v_add_f32_e32 v13, v0, v3
	v_mov_b32_e32 v2, v4
	v_mov_b32_e32 v3, v8
	v_pk_mul_f32 v[2:3], v[52:53], v[2:3]
	v_mov_b32_e32 v8, v5
	v_add_f32_e32 v0, v61, v2
	v_pk_mul_f32 v[4:5], v[52:53], v[8:9]
	v_add_f32_e32 v2, v0, v3
	v_add_f32_e32 v0, v58, v4
	v_add_f32_e32 v0, v0, v5
	v_mov_b32_e32 v4, v22
	v_mov_b32_e32 v5, v20
	v_pk_add_f32 v[4:5], v[18:19], v[4:5] op_sel:[1,0] op_sel_hi:[0,1]
	v_mov_b32_e32 v20, v23
	v_pk_add_f32 v[4:5], v[4:5], v[20:21]
	v_mov_b32_e32 v6, v56
	v_mov_b32_e32 v7, v54
	v_pk_add_f32 v[4:5], v[4:5], v[6:7]
	v_mov_b32_e32 v54, v57
	v_pk_add_f32 v[4:5], v[4:5], v[54:55]
	v_mov_b32_e32 v6, v10
	v_mov_b32_e32 v7, v64
	v_pk_add_f32 v[4:5], v[4:5], v[6:7]
	v_mov_b32_e32 v64, v11
	v_pk_add_f32 v[4:5], v[4:5], v[64:65]
	s_nop 1
	v_mov_b32_dpp v7, v5 quad_perm:[1,0,3,2] row_mask:0xf bank_mask:0xf
	s_nop 0
	s_nop 1
	v_mov_b32_dpp v6, v4 quad_perm:[1,0,3,2] row_mask:0xf bank_mask:0xf
	s_nop 0
	s_nop 1
	v_mov_b32_dpp v3, v14 quad_perm:[1,0,3,2] row_mask:0xf bank_mask:0xf
	s_nop 0
	s_waitcnt lgkmcnt(1)
	v_pk_add_f32 v[4:5], v[4:5], v[6:7]
	s_nop 1
	v_mov_b32_dpp v7, v5 quad_perm:[2,3,0,1] row_mask:0xf bank_mask:0xf
	s_nop 0
	s_nop 1
	v_mov_b32_dpp v6, v4 quad_perm:[2,3,0,1] row_mask:0xf bank_mask:0xf
	s_nop 0
	s_waitcnt lgkmcnt(2)
	v_add_f32_e32 v3, v14, v3
	s_waitcnt lgkmcnt(0)
	v_pk_add_f32 v[4:5], v[4:5], v[6:7]
	s_nop 1
	v_mov_b32_dpp v7, v5 row_shl:4 row_mask:0xf bank_mask:0x5
	v_mov_b32_dpp v7, v5 row_shr:4 row_mask:0xf bank_mask:0xa
	s_nop 0
	s_nop 1
	v_mov_b32_dpp v6, v4 row_shl:4 row_mask:0xf bank_mask:0x5
	v_mov_b32_dpp v6, v4 row_shr:4 row_mask:0xf bank_mask:0xa
	s_nop 0
	s_waitcnt lgkmcnt(0)
	v_pk_add_f32 v[4:5], v[4:5], v[6:7]
	s_nop 1
	v_mov_b32_dpp v7, v5 row_ror:8 row_mask:0xf bank_mask:0xf
	s_nop 0
	s_nop 1
	v_mov_b32_dpp v6, v4 row_ror:8 row_mask:0xf bank_mask:0xf
	s_nop 0
	s_waitcnt lgkmcnt(0)
;     ...
;             for (int e = 0; e < 8; ++e) lg[e] = wave_sum(lg[e]);
;             int e1 = 0; float v1 = lg[0];
; #pragma unroll
;             for (int e = 1; e < 8; ++e) if (lg[e] > v1) { v1 = lg[e]; e1 = e; }
;             int e2 = -1; float v2 = -__builtin_inff();
; #pragma unroll
;             for (int e = 0; e < 8; ++e) if (e != e1 && lg[e] > v2) { v2 = lg[e]; e2 = e; }
	v_pk_add_f32 v[4:5], v[4:5], v[6:7]
	s_nop 1
	v_mov_b32_e32 v7, v5
	v_mov_b32_e32 v79, v5
	s_nop 1
	v_permlane16_swap_b32_e32 v7, v79
	s_nop 1
	v_mov_b32_dpp v7, v79 quad_perm:[0,1,2,3] row_mask:0x5 bank_mask:0xf
	s_nop 0
	s_nop 1
	v_mov_b32_e32 v6, v4
	v_mov_b32_e32 v79, v4
	s_nop 1
	v_permlane16_swap_b32_e32 v6, v79
	s_nop 1
	v_mov_b32_dpp v6, v79 quad_perm:[0,1,2,3] row_mask:0x5 bank_mask:0xf
	s_nop 0
	s_waitcnt lgkmcnt(0)
	v_pk_add_f32 v[4:5], v[4:5], v[6:7]
	s_nop 1
	v_mov_b32_e32 v7, v5
	v_mov_b32_e32 v79, v5
	s_nop 1
	v_permlane32_swap_b32_e32 v7, v79
	s_nop 1
	v_mov_b32_dpp v7, v79 quad_perm:[0,1,2,3] row_mask:0x3 bank_mask:0xf
	s_nop 0
	s_nop 1
	v_mov_b32_e32 v6, v4
	v_mov_b32_e32 v79, v4
	s_nop 1
	v_permlane32_swap_b32_e32 v6, v79
	s_nop 1
	v_mov_b32_dpp v6, v79 quad_perm:[0,1,2,3] row_mask:0x3 bank_mask:0xf
	s_nop 0
	s_waitcnt lgkmcnt(0)
	v_pk_add_f32 v[4:5], v[4:5], v[6:7]
	s_nop 1
	v_mov_b32_dpp v6, v3 quad_perm:[2,3,0,1] row_mask:0xf bank_mask:0xf
	s_nop 0
	v_cmp_gt_f32_e32 vcc, v4, v5
	v_cmp_nlg_f32_e64 s[8:9], s8, v5
	s_waitcnt lgkmcnt(0)
	v_add_f32_e32 v3, v3, v6
	s_nop 1
	v_mov_b32_dpp v6, v3 row_shl:4 row_mask:0xf bank_mask:0x5
	v_mov_b32_dpp v6, v3 row_shr:4 row_mask:0xf bank_mask:0xa
	s_nop 0
	s_waitcnt lgkmcnt(0)
	v_add_f32_e32 v3, v3, v6
	s_nop 1
	v_mov_b32_dpp v6, v3 row_ror:8 row_mask:0xf bank_mask:0xf
	s_nop 0
	s_waitcnt lgkmcnt(0)
	v_add_f32_e32 v3, v3, v6
	s_nop 1
	v_mov_b32_e32 v6, v3
	v_mov_b32_e32 v79, v3
	s_nop 1
	v_permlane16_swap_b32_e32 v6, v79
	s_nop 1
	v_mov_b32_dpp v6, v79 quad_perm:[0,1,2,3] row_mask:0x5 bank_mask:0xf
	s_nop 0
	s_waitcnt lgkmcnt(0)
	v_add_f32_e32 v3, v3, v6
	s_nop 1
	v_mov_b32_e32 v6, v3
	v_mov_b32_e32 v79, v3
	s_nop 1
	v_permlane32_swap_b32_e32 v6, v79
	s_nop 1
	v_mov_b32_dpp v6, v79 quad_perm:[0,1,2,3] row_mask:0x3 bank_mask:0xf
	s_nop 0
	s_waitcnt lgkmcnt(0)
	v_add_f32_e32 v3, v3, v6
	s_nop 1
	v_mov_b32_dpp v6, v15 quad_perm:[1,0,3,2] row_mask:0xf bank_mask:0xf
	s_nop 0
	s_waitcnt lgkmcnt(0)
	v_add_f32_e32 v6, v15, v6
	s_nop 1
	v_mov_b32_dpp v7, v6 quad_perm:[2,3,0,1] row_mask:0xf bank_mask:0xf
	s_nop 0
	s_waitcnt lgkmcnt(0)
	v_add_f32_e32 v6, v6, v7
	s_nop 1
	v_mov_b32_dpp v7, v6 row_shl:4 row_mask:0xf bank_mask:0x5
	v_mov_b32_dpp v7, v6 row_shr:4 row_mask:0xf bank_mask:0xa
	s_nop 0
	s_waitcnt lgkmcnt(0)
	v_add_f32_e32 v6, v6, v7
	s_nop 1
	v_mov_b32_dpp v7, v6 row_ror:8 row_mask:0xf bank_mask:0xf
	s_nop 0
	s_waitcnt lgkmcnt(0)
	v_add_f32_e32 v6, v6, v7
	s_nop 1
	v_mov_b32_e32 v7, v6
	v_mov_b32_e32 v79, v6
	s_nop 1
	v_permlane16_swap_b32_e32 v7, v79
	s_nop 1
	v_mov_b32_dpp v7, v79 quad_perm:[0,1,2,3] row_mask:0x5 bank_mask:0xf
	s_nop 0
	s_waitcnt lgkmcnt(0)
	v_add_f32_e32 v6, v6, v7
	s_nop 1
	v_mov_b32_e32 v7, v6
	v_mov_b32_e32 v79, v6
	s_nop 1
	v_permlane32_swap_b32_e32 v7, v79
	s_nop 1
	v_mov_b32_dpp v7, v79 quad_perm:[0,1,2,3] row_mask:0x3 bank_mask:0xf
	s_nop 0
	s_waitcnt lgkmcnt(0)
	v_add_f32_e32 v7, v6, v7
	s_nop 1
	v_mov_b32_dpp v6, v12 quad_perm:[1,0,3,2] row_mask:0xf bank_mask:0xf
	s_nop 0
	s_waitcnt lgkmcnt(0)
	v_add_f32_e32 v6, v12, v6
	s_nop 1
	v_mov_b32_dpp v8, v6 quad_perm:[2,3,0,1] row_mask:0xf bank_mask:0xf
	s_nop 0
	s_waitcnt lgkmcnt(0)
	v_add_f32_e32 v6, v6, v8
	s_nop 1
	v_mov_b32_dpp v8, v6 row_shl:4 row_mask:0xf bank_mask:0x5
	v_mov_b32_dpp v8, v6 row_shr:4 row_mask:0xf bank_mask:0xa
	s_nop 0
	s_waitcnt lgkmcnt(0)
	v_add_f32_e32 v6, v6, v8
	s_nop 1
	v_mov_b32_dpp v8, v6 row_ror:8 row_mask:0xf bank_mask:0xf
	s_nop 0
	s_waitcnt lgkmcnt(0)
	v_add_f32_e32 v6, v6, v8
	s_nop 1
	v_mov_b32_e32 v8, v6
	v_mov_b32_e32 v79, v6
	s_nop 1
	v_permlane16_swap_b32_e32 v8, v79
	s_nop 1
	v_mov_b32_dpp v8, v79 quad_perm:[0,1,2,3] row_mask:0x5 bank_mask:0xf
	s_nop 0
	s_waitcnt lgkmcnt(0)
	v_add_f32_e32 v6, v6, v8
	s_nop 1
	v_mov_b32_e32 v8, v6
	v_mov_b32_e32 v79, v6
	s_nop 1
	v_permlane32_swap_b32_e32 v8, v79
	s_nop 1
	v_mov_b32_dpp v8, v79 quad_perm:[0,1,2,3] row_mask:0x3 bank_mask:0xf
	s_nop 0
	s_waitcnt lgkmcnt(0)
	v_add_f32_e32 v8, v6, v8
	s_nop 1
	v_mov_b32_dpp v6, v13 quad_perm:[1,0,3,2] row_mask:0xf bank_mask:0xf
	s_nop 0
	s_waitcnt lgkmcnt(0)
	v_add_f32_e32 v6, v13, v6
	s_nop 1
	v_mov_b32_dpp v9, v6 quad_perm:[2,3,0,1] row_mask:0xf bank_mask:0xf
	s_nop 0
	s_waitcnt lgkmcnt(0)
	v_add_f32_e32 v6, v6, v9
	s_nop 1
	v_mov_b32_dpp v9, v6 row_shl:4 row_mask:0xf bank_mask:0x5
	v_mov_b32_dpp v9, v6 row_shr:4 row_mask:0xf bank_mask:0xa
	s_nop 0
	s_waitcnt lgkmcnt(0)
	v_add_f32_e32 v6, v6, v9
	s_nop 1
	v_mov_b32_dpp v9, v6 row_ror:8 row_mask:0xf bank_mask:0xf
	s_nop 0
	s_waitcnt lgkmcnt(0)
	v_add_f32_e32 v6, v6, v9
	s_nop 1
	v_mov_b32_e32 v9, v6
	v_mov_b32_e32 v79, v6
	s_nop 1
	v_permlane16_swap_b32_e32 v9, v79
	s_nop 1
	v_mov_b32_dpp v9, v79 quad_perm:[0,1,2,3] row_mask:0x5 bank_mask:0xf
	s_nop 0
	s_waitcnt lgkmcnt(0)
	v_add_f32_e32 v6, v6, v9
	s_nop 1
	v_mov_b32_e32 v9, v6
	v_mov_b32_e32 v79, v6
	s_nop 1
	v_permlane32_swap_b32_e32 v9, v79
	s_nop 1
	v_mov_b32_dpp v9, v79 quad_perm:[0,1,2,3] row_mask:0x3 bank_mask:0xf
	s_nop 0
	s_waitcnt lgkmcnt(0)
;     ...
;             for (int e = 0; e < 8; ++e) lg[e] = wave_sum(lg[e]);
;             int e1 = 0; float v1 = lg[0];
; #pragma unroll
;             for (int e = 1; e < 8; ++e) if (lg[e] > v1) { v1 = lg[e]; e1 = e; }
;             int e2 = -1; float v2 = -__builtin_inff();
; #pragma unroll
;             for (int e = 0; e < 8; ++e) if (e != e1 && lg[e] > v2) { v2 = lg[e]; e2 = e; }
;             const float g2 = 1.0f / (1.0f + __expf(v1 - v2)), g1 = 1.0f - g2;
;             if (lane == 0) { f32x4 rt; rt[0] = __int_as_float(e1); rt[1] = __int_as_float(e2); rt[2] = g1; rt[3] = g2; route[m] = rt; }
	v_add_f32_e32 v9, v6, v9
	s_nop 1
	v_mov_b32_dpp v6, v2 quad_perm:[1,0,3,2] row_mask:0xf bank_mask:0xf
	s_nop 0
	s_waitcnt lgkmcnt(0)
	v_add_f32_e32 v2, v2, v6
	s_nop 1
	v_mov_b32_dpp v6, v2 quad_perm:[2,3,0,1] row_mask:0xf bank_mask:0xf
	s_nop 0
	s_waitcnt lgkmcnt(0)
	v_add_f32_e32 v2, v2, v6
	s_nop 1
	v_mov_b32_dpp v6, v2 row_shl:4 row_mask:0xf bank_mask:0x5
	v_mov_b32_dpp v6, v2 row_shr:4 row_mask:0xf bank_mask:0xa
	s_nop 0
	s_waitcnt lgkmcnt(0)
	v_add_f32_e32 v2, v2, v6
	s_nop 1
	v_mov_b32_dpp v6, v2 row_ror:8 row_mask:0xf bank_mask:0xf
	s_nop 0
	s_waitcnt lgkmcnt(0)
	v_add_f32_e32 v2, v2, v6
	s_nop 1
	v_mov_b32_e32 v6, v2
	v_mov_b32_e32 v79, v2
	s_nop 1
	v_permlane16_swap_b32_e32 v6, v79
	s_nop 1
	v_mov_b32_dpp v6, v79 quad_perm:[0,1,2,3] row_mask:0x5 bank_mask:0xf
	s_nop 0
	s_waitcnt lgkmcnt(0)
	v_add_f32_e32 v2, v2, v6
	s_nop 1
	v_mov_b32_e32 v6, v2
	v_mov_b32_e32 v79, v2
	s_nop 1
	v_permlane32_swap_b32_e32 v6, v79
	s_nop 1
	v_mov_b32_dpp v6, v79 quad_perm:[0,1,2,3] row_mask:0x3 bank_mask:0xf
	s_nop 0
	s_waitcnt lgkmcnt(0)
	v_add_f32_e32 v10, v2, v6
	s_nop 1
	v_mov_b32_dpp v2, v0 quad_perm:[1,0,3,2] row_mask:0xf bank_mask:0xf
	s_nop 0
	v_cndmask_b32_e32 v6, v5, v4, vcc
	s_waitcnt lgkmcnt(0)
	v_add_f32_e32 v0, v0, v2
	s_nop 1
	v_mov_b32_dpp v2, v0 quad_perm:[2,3,0,1] row_mask:0xf bank_mask:0xf
	s_nop 0
	s_waitcnt lgkmcnt(0)
	v_add_f32_e32 v0, v0, v2
	s_nop 1
	v_mov_b32_dpp v2, v0 row_shl:4 row_mask:0xf bank_mask:0x5
	v_mov_b32_dpp v2, v0 row_shr:4 row_mask:0xf bank_mask:0xa
	s_nop 0
	s_waitcnt lgkmcnt(0)
	v_add_f32_e32 v0, v0, v2
	s_nop 1
	v_mov_b32_dpp v2, v0 row_ror:8 row_mask:0xf bank_mask:0xf
	s_nop 0
	s_waitcnt lgkmcnt(0)
	v_add_f32_e32 v0, v0, v2
	s_nop 1
	v_mov_b32_e32 v2, v0
	v_mov_b32_e32 v79, v0
	s_nop 1
	v_permlane16_swap_b32_e32 v2, v79
	s_nop 1
	v_mov_b32_dpp v2, v79 quad_perm:[0,1,2,3] row_mask:0x5 bank_mask:0xf
	s_nop 0
	s_waitcnt lgkmcnt(0)
	v_add_f32_e32 v0, v0, v2
	s_nop 1
	v_mov_b32_e32 v2, v0
	v_mov_b32_e32 v79, v0
	s_nop 1
	v_permlane32_swap_b32_e32 v2, v79
	s_nop 1
	v_mov_b32_dpp v2, v79 quad_perm:[0,1,2,3] row_mask:0x3 bank_mask:0xf
	s_nop 0
	s_waitcnt lgkmcnt(0)
	v_add_f32_e32 v0, v0, v2
	v_cndmask_b32_e64 v2, 0, 1, vcc
	v_cmp_gt_f32_e32 vcc, v3, v6
	s_nop 1
	v_cndmask_b32_e32 v6, v6, v3, vcc
	v_cndmask_b32_e64 v2, v2, 2, vcc
	v_cmp_gt_f32_e32 vcc, v7, v6
	s_nop 1
	v_cndmask_b32_e32 v6, v6, v7, vcc
	v_cndmask_b32_e64 v2, v2, 3, vcc
	v_cmp_gt_f32_e32 vcc, v8, v6
	s_nop 1
	v_cndmask_b32_e32 v6, v6, v8, vcc
	v_cndmask_b32_e64 v2, v2, 4, vcc
	v_cmp_gt_f32_e32 vcc, v9, v6
	s_nop 1
	v_cndmask_b32_e32 v6, v6, v9, vcc
	v_cmp_gt_f32_e64 s[4:5], v10, v6
	v_cndmask_b32_e64 v2, v2, 5, vcc
	s_nop 0
	v_cndmask_b32_e64 v6, v6, v10, s[4:5]
	v_cndmask_b32_e64 v2, v2, 6, s[4:5]
	v_cmp_ngt_f32_e32 vcc, v0, v6
	s_nop 1
	v_cndmask_b32_e32 v2, 7, v2, vcc
	v_cmp_eq_u32_e64 s[6:7], 0, v2
	s_or_b64 s[6:7], s[6:7], s[8:9]
	s_nop 0
	v_cndmask_b32_e64 v5, v5, v203, s[6:7]
	v_cndmask_b32_e64 v11, 0, -1, s[6:7]
	v_cmp_ne_u32_e64 s[6:7], 1, v2
	v_cmp_gt_f32_e64 s[8:9], v4, v5
	s_and_b64 s[6:7], s[6:7], s[8:9]
	v_cndmask_b32_e64 v4, v5, v4, s[6:7]
	v_cndmask_b32_e64 v11, v11, 1, s[6:7]
	v_cmp_ne_u32_e64 s[6:7], 2, v2
	v_cmp_gt_f32_e64 s[8:9], v3, v4
	s_and_b64 s[6:7], s[6:7], s[8:9]
	v_cndmask_b32_e64 v3, v4, v3, s[6:7]
	v_cndmask_b32_e64 v5, v11, 2, s[6:7]
	v_cmp_ne_u32_e64 s[6:7], 3, v2
	v_cmp_gt_f32_e64 s[8:9], v7, v3
	s_and_b64 s[6:7], s[6:7], s[8:9]
	v_cndmask_b32_e64 v3, v3, v7, s[6:7]
	v_cndmask_b32_e64 v4, v5, 3, s[6:7]
	v_cmp_ne_u32_e64 s[6:7], 4, v2
	v_cmp_gt_f32_e64 s[8:9], v8, v3
	s_and_b64 s[6:7], s[6:7], s[8:9]
	v_cndmask_b32_e64 v3, v3, v8, s[6:7]
	v_cndmask_b32_e64 v4, v4, 4, s[6:7]
	v_cmp_ne_u32_e64 s[6:7], 5, v2
	v_cmp_gt_f32_e64 s[8:9], v9, v3
	s_and_b64 s[6:7], s[6:7], s[8:9]
	v_cndmask_b32_e64 v3, v3, v9, s[6:7]
	v_cndmask_b32_e64 v4, v4, 5, s[6:7]
	s_and_b64 s[6:7], s[4:5], vcc
	v_cmp_ngt_f32_e64 s[4:5], v10, v3
	s_or_b64 s[4:5], s[6:7], s[4:5]
	s_nop 0
	v_cndmask_b32_e64 v5, 6, v4, s[4:5]
	v_cndmask_b32_e64 v4, v10, v3, s[4:5]
	v_cmp_gt_f32_e64 s[4:5], v0, v4
	s_and_b64 s[44:45], vcc, s[4:5]
	v_cndmask_b32_e64 v3, v5, 7, s[44:45]
	s_and_saveexec_b64 s[4:5], s[42:43]
	s_cbranch_execz .LBB0_1060
	v_cndmask_b32_e64 v4, v4, v0, s[44:45]
	v_cndmask_b32_e32 v0, v0, v6, vcc
	v_sub_f32_e32 v0, v0, v4
	v_mul_f32_e32 v0, 0x3fb8aa3b, v0
	v_exp_f32_e32 v0, v0
	s_nop 0
	v_add_f32_e32 v0, 1.0, v0
	v_div_scale_f32 v4, s[6:7], v0, v0, 1.0
	v_rcp_f32_e32 v5, v4
	v_div_scale_f32 v6, vcc, 1.0, v0, 1.0
	v_fma_f32 v7, -v4, v5, 1.0
	v_fmac_f32_e32 v5, v7, v5
	v_mul_f32_e32 v7, v6, v5
	v_fma_f32 v8, -v4, v7, v6
	v_fmac_f32_e32 v7, v8, v5
	v_fma_f32 v4, -v4, v7, v6
	v_div_fmas_f32 v4, v4, v5, v7
	v_div_fixup_f32 v5, v4, v0, 1.0
	v_sub_f32_e32 v4, 1.0, v5
	global_store_dwordx4 v1, v[2:5], s[10:11]
	s_branch .LBB0_1060

;     ...
;             for (int j = 0; j < 4; ++j) v[j] = ld4h(Ysrc + (size_t)m * DM + (lane + 64 * j) * 4);
;         } else {
;             const f32x4 rt = route[m]; const int s1 = slots[2 * m], s2 = slots[2 * m + 1];
;             const float mu1 = st[(size_t)m * 32 + 20], rs1 = st[(size_t)m * 32 + 21];
; #pragma unroll
;             for (int j = 0; j < 4; ++j) { const f32x4 yv1 = ld4h(Ysrc + (size_t)m * DM + (lane + 64 * j) * 4);
;                 const f32x4 xv = (yv1 - mu1) * rs1 * *((const f32x4*)g1 + lane + 64 * j) + *((const f32x4*)b1 + lane + 64 * j);
;                 const unsigned o1 = *((const unsigned*)((const unsigned char*)oslot + (size_t)s1 * DM) + lane + 64 * j), o2 = *((const unsigned*)((const unsigned char*)oslot + (size_t)s2 * DM) + lane + 64 * j);
;                 const unsigned p1 = *((const unsigned*)((const unsigned char*)oslot2 + (size_t)s1 * DM) + lane + 64 * j), p2 = *((const unsigned*)((const unsigned char*)oslot2 + (size_t)s2 * DM) + lane + 64 * j);
;                 const f32x2 a1l = __builtin_amdgcn_cvt_pk_f32_fp8((int)o1, false), a1h = __builtin_amdgcn_cvt_pk_f32_fp8((int)o1, true), b1l = __builtin_amdgcn_cvt_pk_f32_fp8((int)p1, false), b1h = __builtin_amdgcn_cvt_pk_f32_fp8((int)p1, true);
;                 const f32x2 a2l = __builtin_amdgcn_cvt_pk_f32_fp8((int)o2, false), a2h = __builtin_amdgcn_cvt_pk_f32_fp8((int)o2, true), b2l = __builtin_amdgcn_cvt_pk_f32_fp8((int)p2, false), b2h = __builtin_amdgcn_cvt_pk_f32_fp8((int)p2, true);
;                 const float g1s = rt[2] * (1.0f / O8), g2s = rt[3] * (1.0f / O8);
;                 f32x4 r;
;                 r[0] = xv[0] * DN_ALPHA + g1s * (a1l.x + b1l.x) + g2s * (a2l.x + b2l.x);
;                 r[1] = xv[1] * DN_ALPHA + g1s * (a1l.y + b1l.y) + g2s * (a2l.y + b2l.y);
;                 r[2] = xv[2] * DN_ALPHA + g1s * (a1h.x + b1h.x) + g2s * (a2h.x + b2h.x);
;                 r[3] = xv[3] * DN_ALPHA + g1s * (a1h.y + b1h.y) + g2s * (a2h.y + b2h.y);
;                 if constexpr (WRY) st4h((ystream_t*)Ysrc + (size_t)m * DM + (lane + 64 * j) * 4, r);
;                 v[j] = r; }
;         }
;         float s = 0.f;
; #pragma unroll
;         for (int j = 0; j < 4; ++j) s += (v[j][0] + v[j][1]) + (v[j][2] + v[j][3]);
;         const float mean = wave_sum(s) * (1.f / DM); float s2 = 0.f;
; #pragma unroll
.LBB0_1076:
	global_load_dwordx2 v[10:11], v[6:7], off offset:-1024
	global_load_dwordx2 v[16:17], v[6:7], off offset:-512
	global_load_dwordx2 v[34:35], v[6:7], off
	global_load_dwordx2 v[36:37], v[6:7], off offset:512
	s_mov_b32 s4, 0xba800000
	s_waitcnt vmcnt(0)
	v_cvt_f32_f16_sdwa v13, v11 dst_sel:DWORD dst_unused:UNUSED_PAD src0_sel:WORD_1
	v_cvt_f32_f16_sdwa v14, v10 dst_sel:DWORD dst_unused:UNUSED_PAD src0_sel:WORD_1
	v_cvt_f32_f16_e32 v12, v10
	v_cvt_f32_f16_e32 v15, v11
	v_cvt_f32_f16_sdwa v19, v17 dst_sel:DWORD dst_unused:UNUSED_PAD src0_sel:WORD_1
	v_cvt_f32_f16_sdwa v20, v16 dst_sel:DWORD dst_unused:UNUSED_PAD src0_sel:WORD_1
	v_cvt_f32_f16_e32 v18, v16
	v_cvt_f32_f16_e32 v21, v17
	v_cvt_f32_f16_sdwa v0, v35 dst_sel:DWORD dst_unused:UNUSED_PAD src0_sel:WORD_1
	v_cvt_f32_f16_sdwa v22, v34 dst_sel:DWORD dst_unused:UNUSED_PAD src0_sel:WORD_1
	v_cvt_f32_f16_e32 v38, v35
	v_cvt_f32_f16_e32 v24, v34
	v_cvt_f32_f16_sdwa v39, v36 dst_sel:DWORD dst_unused:UNUSED_PAD src0_sel:WORD_1
	v_pk_add_f32 v[12:13], v[14:15], v[12:13]
	v_cvt_f32_f16_sdwa v23, v37 dst_sel:DWORD dst_unused:UNUSED_PAD src0_sel:WORD_1
	v_cvt_f32_f16_e32 v25, v37
	v_cvt_f32_f16_e32 v33, v36
	v_add_f32_e32 v12, v12, v13
	v_add_f32_e32 v32, 0, v12
	v_pk_add_f32 v[12:13], v[20:21], v[18:19]
	v_add_f32_e32 v24, v24, v22
	v_pk_add_f32 v[12:13], v[12:13], v[12:13] op_sel:[0,1] op_sel_hi:[1,0]
	v_add_f32_e32 v22, v38, v0
	v_mov_b32_e32 v13, v39
	v_pk_add_f32 v[12:13], v[32:33], v[12:13]
	v_pk_add_f32 v[14:15], v[24:25], v[22:23]
	s_nop 0
	v_pk_add_f32 v[12:13], v[12:13], v[14:15]
	s_nop 0
	v_add_f32_e32 v0, v12, v13
	s_nop 1
	v_mov_b32_dpp v12, v0 quad_perm:[1,0,3,2] row_mask:0xf bank_mask:0xf
	s_nop 0
	s_waitcnt lgkmcnt(0)
	v_add_f32_e32 v0, v0, v12
	s_nop 1
	v_mov_b32_dpp v12, v0 quad_perm:[2,3,0,1] row_mask:0xf bank_mask:0xf
	s_nop 0
	s_waitcnt lgkmcnt(0)
	v_add_f32_e32 v0, v0, v12
	s_nop 1
	v_mov_b32_dpp v12, v0 row_shl:4 row_mask:0xf bank_mask:0x5
	v_mov_b32_dpp v12, v0 row_shr:4 row_mask:0xf bank_mask:0xa
	s_nop 0
	s_waitcnt lgkmcnt(0)
	v_add_f32_e32 v0, v0, v12
	s_nop 1
	v_mov_b32_dpp v12, v0 row_ror:8 row_mask:0xf bank_mask:0xf
	s_nop 0
	s_waitcnt lgkmcnt(0)
	v_add_f32_e32 v0, v0, v12
	s_nop 1
	v_mov_b32_e32 v12, v0
	v_mov_b32_e32 v44, v0
	s_nop 1
	v_permlane16_swap_b32_e32 v12, v44
	s_nop 1
	v_mov_b32_dpp v12, v44 quad_perm:[0,1,2,3] row_mask:0x5 bank_mask:0xf
	s_nop 0
	s_waitcnt lgkmcnt(0)
	v_add_f32_e32 v0, v0, v12
	s_nop 1
	v_mov_b32_e32 v12, v0
	v_mov_b32_e32 v44, v0
	s_nop 1
	v_permlane32_swap_b32_e32 v12, v44
	s_nop 1
	v_mov_b32_dpp v12, v44 quad_perm:[0,1,2,3] row_mask:0x3 bank_mask:0xf
	s_nop 0
	s_waitcnt lgkmcnt(0)
	v_add_f32_e32 v32, v0, v12
	v_fma_mix_f32 v23, v32, s4, v10 op_sel:[0,0,1] op_sel_hi:[0,0,1]
	v_fma_mix_f32 v22, v32, s4, v10 op_sel_hi:[0,0,1]
	v_fma_mix_f32 v25, v32, s4, v11 op_sel:[0,0,1] op_sel_hi:[0,0,1]
	v_fma_mix_f32 v24, v32, s4, v11 op_sel_hi:[0,0,1]
	v_pk_mul_f32 v[10:11], v[24:25], v[24:25]
	v_pk_mul_f32 v[12:13], v[22:23], v[22:23]
	v_fma_mix_f32 v19, v32, s4, v16 op_sel:[0,0,1] op_sel_hi:[0,0,1]
	v_pk_mov_b32 v[14:15], v[12:13], v[10:11] op_sel:[1,0]
	v_mov_b32_e32 v13, v11
	v_pk_add_f32 v[10:11], v[14:15], v[12:13]
	v_fma_mix_f32 v18, v32, s4, v16 op_sel_hi:[0,0,1]
	v_fma_mix_f32 v21, v32, s4, v17 op_sel:[0,0,1] op_sel_hi:[0,0,1]
	v_fma_mix_f32 v20, v32, s4, v17 op_sel_hi:[0,0,1]
	v_pk_add_f32 v[38:39], v[10:11], v[10:11] op_sel_hi:[0,1]
	v_pk_mul_f32 v[10:11], v[20:21], v[20:21]
	v_pk_mul_f32 v[12:13], v[18:19], v[18:19]
	v_fma_mix_f32 v16, v32, s4, v35 op_sel_hi:[0,0,1]
	v_pk_mov_b32 v[14:15], v[12:13], v[10:11] op_sel:[1,0]
	v_mov_b32_e32 v13, v11
	v_pk_add_f32 v[10:11], v[14:15], v[12:13]
	v_fma_mix_f32 v14, v32, s4, v34 op_sel_hi:[0,0,1]
	v_fma_mix_f32 v15, v32, s4, v34 op_sel:[0,0,1] op_sel_hi:[0,0,1]
	v_mul_f32_e32 v0, v14, v14
	v_fma_mix_f32 v17, v32, s4, v35 op_sel:[0,0,1] op_sel_hi:[0,0,1]
	v_pk_fma_f32 v[34:35], v[14:15], v[14:15], v[0:1] op_sel_hi:[1,1,0]
	v_mul_f32_e32 v0, v16, v16
	v_pk_add_f32 v[40:41], v[10:11], v[10:11] op_sel_hi:[0,1]
	v_pk_fma_f32 v[42:43], v[16:17], v[16:17], v[0:1] op_sel_hi:[1,1,0]
	v_fma_mix_f32 v11, v32, s4, v37 op_sel:[0,0,1] op_sel_hi:[0,0,1]
	v_fma_mix_f32 v10, v32, s4, v37 op_sel_hi:[0,0,1]
	v_fma_mix_f32 v13, v32, s4, v36 op_sel:[0,0,1] op_sel_hi:[0,0,1]
	v_fma_mix_f32 v12, v32, s4, v36 op_sel_hi:[0,0,1]
	v_mul_f32_e32 v34, v12, v12
	v_mul_f32_e32 v42, v13, v13
	v_mul_f32_e32 v38, v10, v10
	v_mul_f32_e32 v40, v11, v11
	v_pk_add_f32 v[34:35], v[34:35], v[42:43]
	v_pk_add_f32 v[36:37], v[38:39], v[40:41]
	s_nop 0
	v_pk_add_f32 v[34:35], v[34:35], v[36:37]
	s_nop 0
	v_add_f32_e32 v0, v34, v35
	global_load_dwordx4 v[34:37], v[2:3], off
	global_load_dwordx4 v[38:41], v[4:5], off
	s_nop 1
	v_mov_b32_dpp v33, v0 quad_perm:[1,0,3,2] row_mask:0xf bank_mask:0xf
	s_nop 0
	s_waitcnt lgkmcnt(0)
; __device__ __forceinline__ unsigned cvt_pk_bf16(float lo, float hi) { unsigned r; asm volatile("v_cvt_pk_bf16_f32 %0, %1, %2" : "=v"(r) : "v"(lo), "v"(hi)); return r; }
; __device__ __forceinline__ unsigned cvt4_fp8(float a, float b, float c, float d) { unsigned w = __builtin_amdgcn_cvt_pk_fp8_f32(a, b, 0u, false); return (unsigned)__builtin_amdgcn_cvt_pk_fp8_f32(c, d, (int)w, true); }
;     ...
;         const float mean = wave_sum(s) * (1.f / DM); float s2 = 0.f;
; #pragma unroll
;         for (int j = 0; j < 4; ++j) { v[j] = v[j] - mean; s2 += (v[j][0] * v[j][0] + v[j][1] * v[j][1]) + (v[j][2] * v[j][2] + v[j][3] * v[j][3]); }
;         const float rstd = __builtin_amdgcn_rsqf(wave_sum(s2) * (1.f / DM) + 1e-5f);
; #pragma unroll
;         for (int j = 0; j < 4; ++j) { const f32x4 gv = *((const f32x4*)g + lane + 64 * j), bv = *((const f32x4*)b + lane + 64 * j);
;             v[j] = v[j] * rstd * gv + bv;
;             if constexpr (!NOX) *((f32x4*)(Xout + (size_t)m * DM) + lane + 64 * j) = v[j];
;             if constexpr (OUT8) { *((unsigned*)((unsigned char*)XB + (size_t)m * DM) + lane + 64 * j) = cvt4_fp8(v[j][0], v[j][1], v[j][2], v[j][3]); }
;             else if (XB) { u32x2 w; w.x = cvt_pk_bf16(v[j][0], v[j][1]); w.y = cvt_pk_bf16(v[j][2], v[j][3]); *((u32x2*)(XB + (size_t)m * DM) + lane + 64 * j) = w; } }
;         if constexpr (NOX) { if (lane == 0) { st[(size_t)m * 32 + stslot] = mean; st[(size_t)m * 32 + stslot + 1] = rstd; } }
	v_add_f32_e32 v0, v0, v33
	s_nop 1
	v_mov_b32_dpp v33, v0 quad_perm:[2,3,0,1] row_mask:0xf bank_mask:0xf
	s_nop 0
	s_waitcnt lgkmcnt(0)
	v_add_f32_e32 v0, v0, v33
	s_nop 1
	v_mov_b32_dpp v33, v0 row_shl:4 row_mask:0xf bank_mask:0x5
	v_mov_b32_dpp v33, v0 row_shr:4 row_mask:0xf bank_mask:0xa
	s_nop 0
	s_waitcnt lgkmcnt(0)
	v_add_f32_e32 v0, v0, v33
	s_nop 1
	v_mov_b32_dpp v33, v0 row_ror:8 row_mask:0xf bank_mask:0xf
	s_nop 0
	s_waitcnt lgkmcnt(0)
	v_add_f32_e32 v0, v0, v33
	s_nop 1
	v_mov_b32_e32 v33, v0
	v_mov_b32_e32 v44, v0
	s_nop 1
	v_permlane16_swap_b32_e32 v33, v44
	s_nop 1
	v_mov_b32_dpp v33, v44 quad_perm:[0,1,2,3] row_mask:0x5 bank_mask:0xf
	s_nop 0
	s_waitcnt lgkmcnt(0)
	v_add_f32_e32 v0, v0, v33
	s_nop 1
	v_mov_b32_e32 v33, v0
	v_mov_b32_e32 v44, v0
	s_nop 1
	v_permlane32_swap_b32_e32 v33, v44
	s_nop 1
	v_mov_b32_dpp v33, v44 quad_perm:[0,1,2,3] row_mask:0x3 bank_mask:0xf
	s_nop 0
	s_waitcnt lgkmcnt(0)
	v_add_f32_e32 v0, v0, v33
	v_fmamk_f32 v0, v0, 0x3a800000, v199
	v_rsq_f32_e32 v0, v0
	v_mov_b32_e32 v33, v1
	v_pk_mul_f32 v[42:43], v[22:23], v[0:1] op_sel_hi:[1,0]
	v_pk_mul_f32 v[22:23], v[24:25], v[0:1] op_sel_hi:[1,0]
	v_pk_mul_f32 v[18:19], v[18:19], v[0:1] op_sel_hi:[1,0]
	v_pk_mul_f32 v[20:21], v[20:21], v[0:1] op_sel_hi:[1,0]
	v_pk_mul_f32 v[14:15], v[14:15], v[0:1] op_sel_hi:[1,0]
	v_pk_mul_f32 v[16:17], v[16:17], v[0:1] op_sel_hi:[1,0]
	v_pk_mul_f32 v[12:13], v[12:13], v[0:1] op_sel_hi:[1,0]
	v_pk_mul_f32 v[10:11], v[10:11], v[0:1] op_sel_hi:[1,0]
	s_waitcnt vmcnt(0)
	v_pk_fma_f32 v[24:25], v[34:35], v[42:43], v[38:39]
	s_nop 0
	v_cvt_pk_fp8_f32 v33, v24, v25
	v_pk_fma_f32 v[22:23], v[36:37], v[22:23], v[40:41]
	s_nop 0
	v_cvt_pk_fp8_f32 v33, v22, v23 op_sel:[0,0,1]
	global_store_dword v[8:9], v33, off offset:-512
	global_load_dwordx4 v[22:25], v[2:3], off offset:1024
	global_load_dwordx4 v[34:37], v[4:5], off offset:1024
	s_waitcnt vmcnt(0)
	v_pk_fma_f32 v[18:19], v[22:23], v[18:19], v[34:35]
	v_mov_b32_e32 v22, v1
	v_cvt_pk_fp8_f32 v22, v18, v19
	v_pk_fma_f32 v[20:21], v[24:25], v[20:21], v[36:37]
	s_nop 0
	v_cvt_pk_fp8_f32 v22, v20, v21 op_sel:[0,0,1]
	global_store_dword v[8:9], v22, off offset:-256
	global_load_dwordx4 v[18:21], v[2:3], off offset:2048
	s_nop 0
	global_load_dwordx4 v[22:25], v[4:5], off offset:2048
	s_waitcnt vmcnt(0)
	v_pk_fma_f32 v[14:15], v[18:19], v[14:15], v[22:23]
	v_mov_b32_e32 v18, v1
	v_cvt_pk_fp8_f32 v18, v14, v15
	v_pk_fma_f32 v[16:17], v[20:21], v[16:17], v[24:25]
	s_nop 0
	v_cvt_pk_fp8_f32 v18, v16, v17 op_sel:[0,0,1]
	global_store_dword v[8:9], v18, off
	global_load_dwordx4 v[14:17], v[2:3], off offset:3072
	s_nop 0
	global_load_dwordx4 v[18:21], v[4:5], off offset:3072
	s_waitcnt vmcnt(0)
	v_pk_fma_f32 v[12:13], v[14:15], v[12:13], v[18:19]
	v_mov_b32_e32 v14, v1
	v_cvt_pk_fp8_f32 v14, v12, v13
	v_pk_fma_f32 v[10:11], v[16:17], v[10:11], v[20:21]
	s_nop 0
	v_cvt_pk_fp8_f32 v14, v10, v11 op_sel:[0,0,1]
	global_store_dword v[8:9], v14, off offset:256
	s_and_saveexec_b64 s[4:5], vcc
	s_cbranch_execz .LBB0_1075
	v_mul_f32_e32 v10, 0x3a800000, v32
	v_mov_b32_e32 v11, v0
	global_store_dwordx2 v1, v[10:11], s[2:3]
	s_branch .LBB0_1075

; __device__ __forceinline__ f32x4 ld4h(const ystream_t* p) { return __builtin_convertvector(*(const h16x4*)p, f32x4); }
; __device__ __forceinline__ void st4h(ystream_t* p, f32x4 v) { *(h16x4*)p = __builtin_convertvector(v, h16x4); }
;     ...
;             const f32x4 rt = route[m]; const int s1 = slots[2 * m], s2 = slots[2 * m + 1];
;             const float mu1 = st[(size_t)m * 32 + 20], rs1 = st[(size_t)m * 32 + 21];
; #pragma unroll
;             for (int j = 0; j < 4; ++j) { const f32x4 yv1 = ld4h(Ysrc + (size_t)m * DM + (lane + 64 * j) * 4);
;                 const f32x4 xv = (yv1 - mu1) * rs1 * *((const f32x4*)g1 + lane + 64 * j) + *((const f32x4*)b1 + lane + 64 * j);
;                 const unsigned o1 = *((const unsigned*)((const unsigned char*)oslot + (size_t)s1 * DM) + lane + 64 * j), o2 = *((const unsigned*)((const unsigned char*)oslot + (size_t)s2 * DM) + lane + 64 * j);
;                 const unsigned p1 = *((const unsigned*)((const unsigned char*)oslot2 + (size_t)s1 * DM) + lane + 64 * j), p2 = *((const unsigned*)((const unsigned char*)oslot2 + (size_t)s2 * DM) + lane + 64 * j);
;                 const f32x2 a1l = __builtin_amdgcn_cvt_pk_f32_fp8((int)o1, false), a1h = __builtin_amdgcn_cvt_pk_f32_fp8((int)o1, true), b1l = __builtin_amdgcn_cvt_pk_f32_fp8((int)p1, false), b1h = __builtin_amdgcn_cvt_pk_f32_fp8((int)p1, true);
;                 const f32x2 a2l = __builtin_amdgcn_cvt_pk_f32_fp8((int)o2, false), a2h = __builtin_amdgcn_cvt_pk_f32_fp8((int)o2, true), b2l = __builtin_amdgcn_cvt_pk_f32_fp8((int)p2, false), b2h = __builtin_amdgcn_cvt_pk_f32_fp8((int)p2, true);
;                 const float g1s = rt[2] * (1.0f / O8), g2s = rt[3] * (1.0f / O8);
;                 f32x4 r;
;                 r[0] = xv[0] * DN_ALPHA + g1s * (a1l.x + b1l.x) + g2s * (a2l.x + b2l.x);
;                 r[1] = xv[1] * DN_ALPHA + g1s * (a1l.y + b1l.y) + g2s * (a2l.y + b2l.y);
;                 r[2] = xv[2] * DN_ALPHA + g1s * (a1h.x + b1h.x) + g2s * (a2h.x + b2h.x);
;                 r[3] = xv[3] * DN_ALPHA + g1s * (a1h.y + b1h.y) + g2s * (a2h.y + b2h.y);
;                 if constexpr (WRY) st4h((ystream_t*)Ysrc + (size_t)m * DM + (lane + 64 * j) * 4, r);
;                 v[j] = r; }
.LBB0_1426:
	s_add_u32 s2, s14, s8
	s_addc_u32 s3, s15, s9
	s_ashr_i32 s1, s0, 31
	s_nop 0
	global_load_dwordx4 v[18:21], v1, s[2:3]
	s_lshl_b64 s[2:3], s[0:1], 2
	s_add_u32 s4, s6, s2
	s_addc_u32 s5, s7, s3
	s_add_u32 s2, s14, s10
	s_addc_u32 s3, s15, s11
	global_load_dwordx2 v[42:43], v200, s[2:3] offset:80
	global_load_dwordx2 v[18:19], v1, s[4:5]
	v_lshl_add_u64 v[40:41], s[14:15], 0, v[14:15]
	s_waitcnt vmcnt(0)
	v_mul_f32_e32 v30, 0x3c800000, v20
	v_mul_f32_e32 v0, 0x3c800000, v21
	v_ashrrev_i32_e32 v25, 31, v19
	v_mov_b32_e32 v24, v19
	v_ashrrev_i32_e32 v23, 31, v18
	v_mov_b32_e32 v22, v18
	v_lshlrev_b64 v[18:19], 10, v[24:25]
	v_lshl_add_u64 v[38:39], v[6:7], 0, v[18:19]
	v_lshl_add_u64 v[32:33], v[8:9], 0, v[18:19]
	global_load_dwordx2 v[18:19], v[40:41], off offset:-1024
	v_lshlrev_b64 v[22:23], 10, v[22:23]
	v_lshl_add_u64 v[36:37], v[6:7], 0, v[22:23]
	v_lshl_add_u64 v[34:35], v[8:9], 0, v[22:23]
	s_waitcnt vmcnt(0)
	v_cvt_f32_f16_sdwa v21, v18 dst_sel:DWORD dst_unused:UNUSED_PAD src0_sel:WORD_1
	v_cvt_f32_f16_e32 v20, v18
	v_cvt_f32_f16_sdwa v22, v19 dst_sel:DWORD dst_unused:UNUSED_PAD src0_sel:WORD_1
	v_cvt_f32_f16_e32 v18, v19
	v_sub_f32_e32 v21, v21, v42
	v_sub_f32_e32 v20, v20, v42
	v_sub_f32_e32 v19, v22, v42
	v_sub_f32_e32 v18, v18, v42
	v_pk_mul_f32 v[26:27], v[42:43], v[20:21] op_sel:[1,0]
	v_pk_mul_f32 v[28:29], v[42:43], v[18:19] op_sel:[1,0]
	global_load_dwordx4 v[18:21], v[2:3], off
	global_load_dwordx4 v[22:25], v[4:5], off
	s_waitcnt vmcnt(0)
	v_pk_fma_f32 v[20:21], v[20:21], v[28:29], v[24:25]
	global_load_dword v24, v[36:37], off
	global_load_dword v31, v[38:39], off
	global_load_dword v28, v[34:35], off
	global_load_dword v56, v[32:33], off
	v_pk_fma_f32 v[18:19], v[18:19], v[26:27], v[22:23]
	s_waitcnt vmcnt(3)
	v_cvt_pk_f32_fp8_e32 v[22:23], v24
	s_waitcnt vmcnt(2)
	v_cvt_pk_f32_fp8_e32 v[50:51], v31
	s_waitcnt vmcnt(1)
	v_cvt_pk_f32_fp8_e32 v[26:27], v28
	s_waitcnt vmcnt(0)
	v_cvt_pk_f32_fp8_e32 v[54:55], v56
	v_cvt_pk_f32_fp8_sdwa v[24:25], v24 src0_sel:WORD_1
	v_cvt_pk_f32_fp8_sdwa v[28:29], v28 src0_sel:WORD_1
	v_pk_add_f32 v[22:23], v[22:23], v[26:27]
	v_cvt_pk_f32_fp8_sdwa v[52:53], v31 src0_sel:WORD_1
	v_cvt_pk_f32_fp8_sdwa v[56:57], v56 src0_sel:WORD_1
	v_pk_mul_f32 v[22:23], v[30:31], v[22:23] op_sel_hi:[0,1]
	v_pk_fma_f32 v[18:19], v[18:19], s[36:37], v[22:23] op_sel_hi:[1,0,1]
	v_pk_add_f32 v[22:23], v[50:51], v[54:55]
	s_nop 0
	v_pk_fma_f32 v[22:23], v[0:1], v[22:23], v[18:19] op_sel_hi:[0,1,1]
	v_pk_add_f32 v[18:19], v[24:25], v[28:29]
	s_nop 0
	v_pk_mul_f32 v[18:19], v[30:31], v[18:19] op_sel_hi:[0,1]
	v_pk_fma_f32 v[18:19], v[20:21], s[36:37], v[18:19] op_sel_hi:[1,0,1]
	v_pk_add_f32 v[20:21], v[52:53], v[56:57]
	s_nop 0
	v_pk_fma_f32 v[24:25], v[0:1], v[20:21], v[18:19] op_sel_hi:[0,1,1]
	v_cvt_pk_f16_f32 v19, v24, v25
	v_cvt_pk_f16_f32 v18, v22, v23
	global_store_dwordx2 v[40:41], v[18:19], off offset:-1024
	global_load_dwordx2 v[18:19], v[40:41], off offset:-512
	s_waitcnt vmcnt(0)
	v_cvt_f32_f16_sdwa v21, v18 dst_sel:DWORD dst_unused:UNUSED_PAD src0_sel:WORD_1
	v_cvt_f32_f16_e32 v20, v18
	v_cvt_f32_f16_sdwa v26, v19 dst_sel:DWORD dst_unused:UNUSED_PAD src0_sel:WORD_1
	v_cvt_f32_f16_e32 v18, v19
	v_sub_f32_e32 v21, v21, v42
	v_sub_f32_e32 v20, v20, v42
	v_sub_f32_e32 v19, v26, v42
	v_sub_f32_e32 v18, v18, v42
	v_pk_mul_f32 v[50:51], v[42:43], v[20:21] op_sel:[1,0]
	v_pk_mul_f32 v[52:53], v[42:43], v[18:19] op_sel:[1,0]
	global_load_dwordx4 v[18:21], v[2:3], off offset:1024
	global_load_dwordx4 v[26:29], v[4:5], off offset:1024
	s_waitcnt vmcnt(0)
	v_pk_fma_f32 v[20:21], v[20:21], v[52:53], v[28:29]
	global_load_dword v28, v[36:37], off offset:256
	global_load_dword v31, v[38:39], off offset:256
	global_load_dword v52, v[34:35], off offset:256
	global_load_dword v60, v[32:33], off offset:256
	v_pk_fma_f32 v[18:19], v[18:19], v[50:51], v[26:27]
	s_waitcnt vmcnt(3)
	v_cvt_pk_f32_fp8_e32 v[26:27], v28
	s_waitcnt vmcnt(2)
	v_cvt_pk_f32_fp8_e32 v[54:55], v31
	s_waitcnt vmcnt(1)
	v_cvt_pk_f32_fp8_e32 v[50:51], v52
	s_waitcnt vmcnt(0)
	v_cvt_pk_f32_fp8_e32 v[58:59], v60
	v_cvt_pk_f32_fp8_sdwa v[28:29], v28 src0_sel:WORD_1
	v_cvt_pk_f32_fp8_sdwa v[52:53], v52 src0_sel:WORD_1
	v_pk_add_f32 v[26:27], v[26:27], v[50:51]
	v_cvt_pk_f32_fp8_sdwa v[56:57], v31 src0_sel:WORD_1
	v_cvt_pk_f32_fp8_sdwa v[60:61], v60 src0_sel:WORD_1
	v_pk_mul_f32 v[26:27], v[30:31], v[26:27] op_sel_hi:[0,1]
	v_pk_fma_f32 v[18:19], v[18:19], s[36:37], v[26:27] op_sel_hi:[1,0,1]
	v_pk_add_f32 v[26:27], v[54:55], v[58:59]
	s_nop 0
	v_pk_fma_f32 v[18:19], v[0:1], v[26:27], v[18:19] op_sel_hi:[0,1,1]
	v_pk_add_f32 v[26:27], v[28:29], v[52:53]
	s_nop 0
	v_pk_mul_f32 v[26:27], v[30:31], v[26:27] op_sel_hi:[0,1]
	v_pk_fma_f32 v[20:21], v[20:21], s[36:37], v[26:27] op_sel_hi:[1,0,1]
	v_pk_add_f32 v[26:27], v[56:57], v[60:61]
	s_nop 0
	v_pk_fma_f32 v[20:21], v[0:1], v[26:27], v[20:21] op_sel_hi:[0,1,1]
	v_cvt_pk_f16_f32 v27, v20, v21
	v_cvt_pk_f16_f32 v26, v18, v19
	global_store_dwordx2 v[40:41], v[26:27], off offset:-512
	global_load_dwordx2 v[26:27], v[40:41], off
	s_waitcnt vmcnt(0)
	v_cvt_f32_f16_sdwa v29, v26 dst_sel:DWORD dst_unused:UNUSED_PAD src0_sel:WORD_1
	v_cvt_f32_f16_e32 v28, v26
	v_cvt_f32_f16_sdwa v31, v27 dst_sel:DWORD dst_unused:UNUSED_PAD src0_sel:WORD_1
	v_cvt_f32_f16_e32 v26, v27
	v_sub_f32_e32 v29, v29, v42
	v_sub_f32_e32 v28, v28, v42
	v_sub_f32_e32 v27, v31, v42
	v_sub_f32_e32 v26, v26, v42
	v_pk_mul_f32 v[54:55], v[42:43], v[28:29] op_sel:[1,0]
	v_pk_mul_f32 v[56:57], v[42:43], v[26:27] op_sel:[1,0]
	global_load_dwordx4 v[26:29], v[2:3], off offset:2048
	global_load_dwordx4 v[50:53], v[4:5], off offset:2048
	s_waitcnt vmcnt(0)
; __device__ __forceinline__ f32x4 ld4h(const ystream_t* p) { return __builtin_convertvector(*(const h16x4*)p, f32x4); }
; __device__ __forceinline__ void st4h(ystream_t* p, f32x4 v) { *(h16x4*)p = __builtin_convertvector(v, h16x4); }
;     ...
;             for (int j = 0; j < 4; ++j) { const f32x4 yv1 = ld4h(Ysrc + (size_t)m * DM + (lane + 64 * j) * 4);
;                 const f32x4 xv = (yv1 - mu1) * rs1 * *((const f32x4*)g1 + lane + 64 * j) + *((const f32x4*)b1 + lane + 64 * j);
;                 const unsigned o1 = *((const unsigned*)((const unsigned char*)oslot + (size_t)s1 * DM) + lane + 64 * j), o2 = *((const unsigned*)((const unsigned char*)oslot + (size_t)s2 * DM) + lane + 64 * j);
;                 const unsigned p1 = *((const unsigned*)((const unsigned char*)oslot2 + (size_t)s1 * DM) + lane + 64 * j), p2 = *((const unsigned*)((const unsigned char*)oslot2 + (size_t)s2 * DM) + lane + 64 * j);
;                 const f32x2 a1l = __builtin_amdgcn_cvt_pk_f32_fp8((int)o1, false), a1h = __builtin_amdgcn_cvt_pk_f32_fp8((int)o1, true), b1l = __builtin_amdgcn_cvt_pk_f32_fp8((int)p1, false), b1h = __builtin_amdgcn_cvt_pk_f32_fp8((int)p1, true);
;                 const f32x2 a2l = __builtin_amdgcn_cvt_pk_f32_fp8((int)o2, false), a2h = __builtin_amdgcn_cvt_pk_f32_fp8((int)o2, true), b2l = __builtin_amdgcn_cvt_pk_f32_fp8((int)p2, false), b2h = __builtin_amdgcn_cvt_pk_f32_fp8((int)p2, true);
;                 const float g1s = rt[2] * (1.0f / O8), g2s = rt[3] * (1.0f / O8);
;                 f32x4 r;
;                 r[0] = xv[0] * DN_ALPHA + g1s * (a1l.x + b1l.x) + g2s * (a2l.x + b2l.x);
;                 r[1] = xv[1] * DN_ALPHA + g1s * (a1l.y + b1l.y) + g2s * (a2l.y + b2l.y);
;                 r[2] = xv[2] * DN_ALPHA + g1s * (a1h.x + b1h.x) + g2s * (a2h.x + b2h.x);
;                 r[3] = xv[3] * DN_ALPHA + g1s * (a1h.y + b1h.y) + g2s * (a2h.y + b2h.y);
;                 if constexpr (WRY) st4h((ystream_t*)Ysrc + (size_t)m * DM + (lane + 64 * j) * 4, r);
;                 v[j] = r; }
;         }
;         float s = 0.f;
; #pragma unroll
;         for (int j = 0; j < 4; ++j) s += (v[j][0] + v[j][1]) + (v[j][2] + v[j][3]);
;         const float mean = wave_sum(s) * (1.f / DM); float s2 = 0.f;
	v_pk_fma_f32 v[28:29], v[28:29], v[56:57], v[52:53]
	global_load_dword v31, v[36:37], off offset:512
	global_load_dword v60, v[38:39], off offset:512
	global_load_dword v56, v[34:35], off offset:512
	global_load_dword v64, v[32:33], off offset:512
	v_pk_fma_f32 v[26:27], v[26:27], v[54:55], v[50:51]
	s_waitcnt vmcnt(3)
	v_cvt_pk_f32_fp8_e32 v[50:51], v31
	s_waitcnt vmcnt(2)
	v_cvt_pk_f32_fp8_e32 v[58:59], v60
	s_waitcnt vmcnt(1)
	v_cvt_pk_f32_fp8_e32 v[54:55], v56
	s_waitcnt vmcnt(0)
	v_cvt_pk_f32_fp8_e32 v[62:63], v64
	v_cvt_pk_f32_fp8_sdwa v[52:53], v31 src0_sel:WORD_1
	v_cvt_pk_f32_fp8_sdwa v[56:57], v56 src0_sel:WORD_1
	v_pk_add_f32 v[50:51], v[50:51], v[54:55]
	v_cvt_pk_f32_fp8_sdwa v[60:61], v60 src0_sel:WORD_1
	v_cvt_pk_f32_fp8_sdwa v[64:65], v64 src0_sel:WORD_1
	v_pk_mul_f32 v[50:51], v[30:31], v[50:51] op_sel_hi:[0,1]
	v_pk_fma_f32 v[26:27], v[26:27], s[36:37], v[50:51] op_sel_hi:[1,0,1]
	v_pk_add_f32 v[50:51], v[58:59], v[62:63]
	s_nop 0
	v_pk_fma_f32 v[26:27], v[0:1], v[50:51], v[26:27] op_sel_hi:[0,1,1]
	v_pk_add_f32 v[50:51], v[52:53], v[56:57]
	s_nop 0
	v_pk_mul_f32 v[50:51], v[30:31], v[50:51] op_sel_hi:[0,1]
	v_pk_fma_f32 v[28:29], v[28:29], s[36:37], v[50:51] op_sel_hi:[1,0,1]
	v_pk_add_f32 v[50:51], v[60:61], v[64:65]
	s_nop 0
	v_pk_fma_f32 v[28:29], v[0:1], v[50:51], v[28:29] op_sel_hi:[0,1,1]
	v_cvt_pk_f16_f32 v51, v28, v29
	v_cvt_pk_f16_f32 v50, v26, v27
	global_store_dwordx2 v[40:41], v[50:51], off
	global_load_dwordx2 v[50:51], v[40:41], off offset:512
	s_waitcnt vmcnt(0)
	v_cvt_f32_f16_sdwa v31, v50 dst_sel:DWORD dst_unused:UNUSED_PAD src0_sel:WORD_1
	v_cvt_f32_f16_e32 v52, v50
	v_cvt_f32_f16_sdwa v53, v51 dst_sel:DWORD dst_unused:UNUSED_PAD src0_sel:WORD_1
	v_cvt_f32_f16_e32 v50, v51
	v_sub_f32_e32 v52, v52, v42
	v_sub_f32_e32 v51, v53, v42
	v_sub_f32_e32 v50, v50, v42
	v_sub_f32_e32 v53, v31, v42
	v_pk_mul_f32 v[58:59], v[42:43], v[52:53] op_sel:[1,0]
	v_pk_mul_f32 v[42:43], v[42:43], v[50:51] op_sel:[1,0]
	global_load_dwordx4 v[50:53], v[2:3], off offset:3072
	global_load_dwordx4 v[54:57], v[4:5], off offset:3072
	s_waitcnt vmcnt(0)
	v_pk_fma_f32 v[50:51], v[50:51], v[58:59], v[54:55]
	global_load_dword v31, v[36:37], off offset:768
	global_load_dword v54, v[38:39], off offset:768
	s_nop 0
	global_load_dword v38, v[34:35], off offset:768
	global_load_dword v58, v[32:33], off offset:768
	v_pk_fma_f32 v[42:43], v[52:53], v[42:43], v[56:57]
	s_waitcnt vmcnt(3)
	v_cvt_pk_f32_fp8_e32 v[32:33], v31
	v_cvt_pk_f32_fp8_sdwa v[34:35], v31 src0_sel:WORD_1
	s_waitcnt vmcnt(1)
	v_cvt_pk_f32_fp8_e32 v[36:37], v38
	v_cvt_pk_f32_fp8_sdwa v[38:39], v38 src0_sel:WORD_1
	v_cvt_pk_f32_fp8_e32 v[52:53], v54
	v_cvt_pk_f32_fp8_sdwa v[54:55], v54 src0_sel:WORD_1
	s_waitcnt vmcnt(0)
	v_cvt_pk_f32_fp8_e32 v[56:57], v58
	v_cvt_pk_f32_fp8_sdwa v[58:59], v58 src0_sel:WORD_1
	v_pk_add_f32 v[32:33], v[32:33], v[36:37]
	v_pk_add_f32 v[34:35], v[34:35], v[38:39]
	v_pk_mul_f32 v[32:33], v[30:31], v[32:33] op_sel_hi:[0,1]
	v_pk_mul_f32 v[30:31], v[30:31], v[34:35] op_sel_hi:[0,1]
	v_pk_fma_f32 v[32:33], v[50:51], s[36:37], v[32:33] op_sel_hi:[1,0,1]
	v_pk_add_f32 v[36:37], v[52:53], v[56:57]
	v_pk_fma_f32 v[30:31], v[42:43], s[36:37], v[30:31] op_sel_hi:[1,0,1]
	v_pk_add_f32 v[34:35], v[54:55], v[58:59]
	v_pk_fma_f32 v[32:33], v[0:1], v[36:37], v[32:33] op_sel_hi:[0,1,1]
	v_pk_fma_f32 v[30:31], v[0:1], v[34:35], v[30:31] op_sel_hi:[0,1,1]
	v_cvt_pk_f16_f32 v35, v30, v31
	v_cvt_pk_f16_f32 v34, v32, v33
	global_store_dwordx2 v[40:41], v[34:35], off offset:512
	v_mov_b32_e32 v34, v22
	v_mov_b32_e32 v35, v24
	v_mov_b32_e32 v36, v23
	v_mov_b32_e32 v37, v25
	v_pk_add_f32 v[34:35], v[34:35], v[36:37]
	v_mov_b32_e32 v36, v18
	v_mov_b32_e32 v37, v20
	v_mov_b32_e32 v38, v19
	v_mov_b32_e32 v39, v21
	v_pk_add_f32 v[36:37], v[36:37], v[38:39]
	v_add_f32_e32 v0, v34, v35
	v_pk_add_f32 v[36:37], v[36:37], v[36:37] op_sel:[0,1] op_sel_hi:[1,0]
	v_pk_add_f32 v[38:39], v[26:27], v[26:27] op_sel:[0,1] op_sel_hi:[1,0]
	v_pk_add_f32 v[40:41], v[28:29], v[28:29] op_sel:[0,1] op_sel_hi:[1,0]
	v_add_f32_e32 v34, 0, v0
	v_mov_b32_e32 v35, v32
	v_mov_b32_e32 v37, v33
	v_mov_b32_e32 v39, v30
	v_mov_b32_e32 v41, v31
	v_pk_add_f32 v[34:35], v[34:35], v[36:37]
	v_pk_add_f32 v[36:37], v[38:39], v[40:41]
	s_nop 0
	v_pk_add_f32 v[34:35], v[34:35], v[36:37]
	s_nop 0
	v_add_f32_e32 v0, v34, v35
	s_nop 1
	v_mov_b32_dpp v34, v0 quad_perm:[1,0,3,2] row_mask:0xf bank_mask:0xf
	s_nop 0
	s_waitcnt lgkmcnt(0)
	v_add_f32_e32 v0, v0, v34
	s_nop 1
	v_mov_b32_dpp v34, v0 quad_perm:[2,3,0,1] row_mask:0xf bank_mask:0xf
	s_nop 0
	s_waitcnt lgkmcnt(0)
	v_add_f32_e32 v0, v0, v34
	s_nop 1
	v_mov_b32_dpp v34, v0 row_shl:4 row_mask:0xf bank_mask:0x5
	v_mov_b32_dpp v34, v0 row_shr:4 row_mask:0xf bank_mask:0xa
	s_nop 0
	s_waitcnt lgkmcnt(0)
	v_add_f32_e32 v0, v0, v34
	s_nop 1
	v_mov_b32_dpp v34, v0 row_ror:8 row_mask:0xf bank_mask:0xf
	s_nop 0
	s_waitcnt lgkmcnt(0)
	v_add_f32_e32 v0, v0, v34
	s_nop 1
	v_mov_b32_e32 v34, v0
	v_mov_b32_e32 v37, v0
	s_nop 1
	v_permlane16_swap_b32_e32 v34, v37
	s_nop 1
	v_mov_b32_dpp v34, v37 quad_perm:[0,1,2,3] row_mask:0x5 bank_mask:0xf
	s_nop 0
	s_waitcnt lgkmcnt(0)
; __device__ __forceinline__ unsigned cvt_pk_bf16(float lo, float hi) { unsigned r; asm volatile("v_cvt_pk_bf16_f32 %0, %1, %2" : "=v"(r) : "v"(lo), "v"(hi)); return r; }
; __device__ __forceinline__ unsigned cvt4_fp8(float a, float b, float c, float d) { unsigned w = __builtin_amdgcn_cvt_pk_fp8_f32(a, b, 0u, false); return (unsigned)__builtin_amdgcn_cvt_pk_fp8_f32(c, d, (int)w, true); }
;     ...
;         float s = 0.f;
; #pragma unroll
;         for (int j = 0; j < 4; ++j) s += (v[j][0] + v[j][1]) + (v[j][2] + v[j][3]);
;         const float mean = wave_sum(s) * (1.f / DM); float s2 = 0.f;
; #pragma unroll
;         for (int j = 0; j < 4; ++j) { v[j] = v[j] - mean; s2 += (v[j][0] * v[j][0] + v[j][1] * v[j][1]) + (v[j][2] * v[j][2] + v[j][3] * v[j][3]); }
;         const float rstd = __builtin_amdgcn_rsqf(wave_sum(s2) * (1.f / DM) + 1e-5f);
; #pragma unroll
;         for (int j = 0; j < 4; ++j) { const f32x4 gv = *((const f32x4*)g + lane + 64 * j), bv = *((const f32x4*)b + lane + 64 * j);
;             v[j] = v[j] * rstd * gv + bv;
;             if constexpr (!NOX) *((f32x4*)(Xout + (size_t)m * DM) + lane + 64 * j) = v[j];
;             if constexpr (OUT8) { *((unsigned*)((unsigned char*)XB + (size_t)m * DM) + lane + 64 * j) = cvt4_fp8(v[j][0], v[j][1], v[j][2], v[j][3]); }
;             else if (XB) { u32x2 w; w.x = cvt_pk_bf16(v[j][0], v[j][1]); w.y = cvt_pk_bf16(v[j][2], v[j][3]); *((u32x2*)(XB + (size_t)m * DM) + lane + 64 * j) = w; } }
;         if constexpr (NOX) { if (lane == 0) { st[(size_t)m * 32 + stslot] = mean; st[(size_t)m * 32 + stslot + 1] = rstd; } }
	v_add_f32_e32 v0, v0, v34
	s_nop 1
	v_mov_b32_e32 v34, v0
	v_mov_b32_e32 v37, v0
	s_nop 1
	v_permlane32_swap_b32_e32 v34, v37
	s_nop 1
	v_mov_b32_dpp v34, v37 quad_perm:[0,1,2,3] row_mask:0x3 bank_mask:0xf
	s_nop 0
	s_waitcnt lgkmcnt(0)
	v_add_f32_e32 v36, v0, v34
	v_fmamk_f32 v23, v36, 0xba800000, v23
	v_fmac_f32_e32 v22, 0xba800000, v36
	v_fmamk_f32 v25, v36, 0xba800000, v25
	v_fmac_f32_e32 v24, 0xba800000, v36
	v_pk_mul_f32 v[34:35], v[24:25], v[24:25]
	v_pk_mul_f32 v[38:39], v[22:23], v[22:23]
	v_fmamk_f32 v19, v36, 0xba800000, v19
	v_pk_mov_b32 v[40:41], v[38:39], v[34:35] op_sel:[1,0]
	v_mov_b32_e32 v39, v35
	v_fmac_f32_e32 v18, 0xba800000, v36
	v_fmamk_f32 v21, v36, 0xba800000, v21
	v_fmac_f32_e32 v20, 0xba800000, v36
	v_pk_add_f32 v[34:35], v[40:41], v[38:39]
	v_pk_mul_f32 v[38:39], v[20:21], v[20:21]
	v_pk_mul_f32 v[40:41], v[18:19], v[18:19]
	v_fmac_f32_e32 v26, 0xba800000, v36
	v_pk_mov_b32 v[42:43], v[40:41], v[38:39] op_sel:[1,0]
	v_mov_b32_e32 v41, v39
	v_fmamk_f32 v27, v36, 0xba800000, v27
	v_fmac_f32_e32 v28, 0xba800000, v36
	v_mul_f32_e32 v0, v26, v26
	v_pk_add_f32 v[38:39], v[42:43], v[40:41]
	v_fmamk_f32 v29, v36, 0xba800000, v29
	v_pk_fma_f32 v[40:41], v[26:27], v[26:27], v[0:1] op_sel_hi:[1,1,0]
	v_mul_f32_e32 v0, v28, v28
	v_pk_add_f32 v[34:35], v[34:35], v[34:35] op_sel_hi:[0,1]
	v_pk_add_f32 v[38:39], v[38:39], v[38:39] op_sel_hi:[0,1]
	v_pk_fma_f32 v[42:43], v[28:29], v[28:29], v[0:1] op_sel_hi:[1,1,0]
	v_fmamk_f32 v31, v36, 0xba800000, v31
	v_fmac_f32_e32 v30, 0xba800000, v36
	v_fmamk_f32 v33, v36, 0xba800000, v33
	v_fmac_f32_e32 v32, 0xba800000, v36
	v_mul_f32_e32 v40, v32, v32
	v_mul_f32_e32 v42, v33, v33
	v_mul_f32_e32 v34, v30, v30
	v_mul_f32_e32 v38, v31, v31
	v_pk_add_f32 v[40:41], v[40:41], v[42:43]
	v_pk_add_f32 v[34:35], v[34:35], v[38:39]
	s_nop 0
	v_pk_add_f32 v[34:35], v[40:41], v[34:35]
	global_load_dwordx4 v[38:41], v[10:11], off
	global_load_dwordx4 v[50:53], v[12:13], off
	v_add_f32_e32 v0, v34, v35
	s_nop 1
	v_mov_b32_dpp v34, v0 quad_perm:[1,0,3,2] row_mask:0xf bank_mask:0xf
	s_nop 0
	s_waitcnt lgkmcnt(0)
	v_add_f32_e32 v0, v0, v34
	s_nop 1
	v_mov_b32_dpp v34, v0 quad_perm:[2,3,0,1] row_mask:0xf bank_mask:0xf
	s_nop 0
	s_waitcnt lgkmcnt(0)
	v_add_f32_e32 v0, v0, v34
	s_nop 1
	v_mov_b32_dpp v34, v0 row_shl:4 row_mask:0xf bank_mask:0x5
	v_mov_b32_dpp v34, v0 row_shr:4 row_mask:0xf bank_mask:0xa
	s_nop 0
	s_waitcnt lgkmcnt(0)
	v_add_f32_e32 v0, v0, v34
	s_nop 1
	v_mov_b32_dpp v34, v0 row_ror:8 row_mask:0xf bank_mask:0xf
	s_nop 0
	s_waitcnt lgkmcnt(0)
	v_add_f32_e32 v0, v0, v34
	s_nop 1
	v_mov_b32_e32 v34, v0
	v_mov_b32_e32 v37, v0
	s_nop 1
	v_permlane16_swap_b32_e32 v34, v37
	s_nop 1
	v_mov_b32_dpp v34, v37 quad_perm:[0,1,2,3] row_mask:0x5 bank_mask:0xf
	s_nop 0
	s_waitcnt lgkmcnt(0)
	v_add_f32_e32 v0, v0, v34
	s_nop 1
	v_mov_b32_e32 v34, v0
	v_mov_b32_e32 v37, v0
	s_nop 1
	v_permlane32_swap_b32_e32 v34, v37
	s_nop 1
	v_mov_b32_dpp v34, v37 quad_perm:[0,1,2,3] row_mask:0x3 bank_mask:0xf
	s_nop 0
	s_waitcnt lgkmcnt(0)
	v_add_f32_e32 v0, v0, v34
	v_fmamk_f32 v0, v0, 0x3a800000, v199
	v_rsq_f32_e32 v0, v0
	v_lshl_add_u64 v[34:35], s[14:15], 0, v[16:17]
	v_pk_mul_f32 v[22:23], v[22:23], v[0:1] op_sel_hi:[1,0]
	v_pk_mul_f32 v[24:25], v[24:25], v[0:1] op_sel_hi:[1,0]
	v_pk_mul_f32 v[26:27], v[26:27], v[0:1] op_sel_hi:[1,0]
	v_pk_mul_f32 v[28:29], v[28:29], v[0:1] op_sel_hi:[1,0]
	s_waitcnt vmcnt(0)
	v_pk_fma_f32 v[22:23], v[38:39], v[22:23], v[50:51]
	v_pk_fma_f32 v[24:25], v[40:41], v[24:25], v[52:53]
	v_cvt_pk_bf16_f32 v22, v22, v23
	v_pk_mul_f32 v[38:39], v[20:21], v[0:1] op_sel_hi:[1,0]
	v_cvt_pk_bf16_f32 v23, v24, v25
	global_store_dwordx2 v[34:35], v[22:23], off offset:-1024
	v_pk_mul_f32 v[40:41], v[18:19], v[0:1] op_sel_hi:[1,0]
	global_load_dwordx4 v[18:21], v[10:11], off offset:1024
	global_load_dwordx4 v[22:25], v[12:13], off offset:1024
	s_waitcnt vmcnt(0)
	v_pk_fma_f32 v[18:19], v[18:19], v[40:41], v[22:23]
	v_pk_fma_f32 v[20:21], v[20:21], v[38:39], v[24:25]
	v_cvt_pk_bf16_f32 v18, v18, v19
	s_nop 0
	v_cvt_pk_bf16_f32 v19, v20, v21
	global_store_dwordx2 v[34:35], v[18:19], off offset:-512
	global_load_dwordx4 v[18:21], v[10:11], off offset:2048
	s_nop 0
	global_load_dwordx4 v[22:25], v[12:13], off offset:2048
	s_waitcnt vmcnt(0)
	v_pk_fma_f32 v[18:19], v[18:19], v[26:27], v[22:23]
	v_pk_fma_f32 v[20:21], v[20:21], v[28:29], v[24:25]
	v_cvt_pk_bf16_f32 v18, v18, v19
	v_pk_mul_f32 v[28:29], v[32:33], v[0:1] op_sel_hi:[1,0]
	v_cvt_pk_bf16_f32 v19, v20, v21
	global_store_dwordx2 v[34:35], v[18:19], off
	global_load_dwordx4 v[18:21], v[10:11], off offset:3072
	s_nop 0
	global_load_dwordx4 v[22:25], v[12:13], off offset:3072
	v_pk_mul_f32 v[26:27], v[30:31], v[0:1] op_sel_hi:[1,0]
	s_waitcnt vmcnt(0)
	v_pk_fma_f32 v[18:19], v[18:19], v[28:29], v[22:23]
	v_pk_fma_f32 v[20:21], v[20:21], v[26:27], v[24:25]
	v_cvt_pk_bf16_f32 v18, v18, v19
	s_nop 0
	v_cvt_pk_bf16_f32 v19, v20, v21
	global_store_dwordx2 v[34:35], v[18:19], off offset:512
	s_and_saveexec_b64 s[4:5], vcc
	s_cbranch_execz .LBB0_1425
	v_mul_f32_e32 v18, 0x3a800000, v36
	v_mov_b32_e32 v19, v0
	global_store_dwordx2 v200, v[18:19], s[2:3] offset:88
	s_branch .LBB0_1425

; __device__ __forceinline__ f32x4 ld4h(const ystream_t* p) { return __builtin_convertvector(*(const h16x4*)p, f32x4); }
; __device__ __forceinline__ void st4h(ystream_t* p, f32x4 v) { *(h16x4*)p = __builtin_convertvector(v, h16x4); }
;     ...
;             const f32x4 rt = route[m]; const int s1 = slots[2 * m], s2 = slots[2 * m + 1];
;             const float mu1 = st[(size_t)m * 32 + 20], rs1 = st[(size_t)m * 32 + 21];
; #pragma unroll
;             for (int j = 0; j < 4; ++j) { const f32x4 yv1 = ld4h(Ysrc + (size_t)m * DM + (lane + 64 * j) * 4);
;                 const f32x4 xv = (yv1 - mu1) * rs1 * *((const f32x4*)g1 + lane + 64 * j) + *((const f32x4*)b1 + lane + 64 * j);
;                 const unsigned o1 = *((const unsigned*)((const unsigned char*)oslot + (size_t)s1 * DM) + lane + 64 * j), o2 = *((const unsigned*)((const unsigned char*)oslot + (size_t)s2 * DM) + lane + 64 * j);
;                 const unsigned p1 = *((const unsigned*)((const unsigned char*)oslot2 + (size_t)s1 * DM) + lane + 64 * j), p2 = *((const unsigned*)((const unsigned char*)oslot2 + (size_t)s2 * DM) + lane + 64 * j);
;                 const f32x2 a1l = __builtin_amdgcn_cvt_pk_f32_fp8((int)o1, false), a1h = __builtin_amdgcn_cvt_pk_f32_fp8((int)o1, true), b1l = __builtin_amdgcn_cvt_pk_f32_fp8((int)p1, false), b1h = __builtin_amdgcn_cvt_pk_f32_fp8((int)p1, true);
;                 const f32x2 a2l = __builtin_amdgcn_cvt_pk_f32_fp8((int)o2, false), a2h = __builtin_amdgcn_cvt_pk_f32_fp8((int)o2, true), b2l = __builtin_amdgcn_cvt_pk_f32_fp8((int)p2, false), b2h = __builtin_amdgcn_cvt_pk_f32_fp8((int)p2, true);
;                 const float g1s = rt[2] * (1.0f / O8), g2s = rt[3] * (1.0f / O8);
;                 f32x4 r;
;                 r[0] = xv[0] * DN_ALPHA + g1s * (a1l.x + b1l.x) + g2s * (a2l.x + b2l.x);
;                 r[1] = xv[1] * DN_ALPHA + g1s * (a1l.y + b1l.y) + g2s * (a2l.y + b2l.y);
;                 r[2] = xv[2] * DN_ALPHA + g1s * (a1h.x + b1h.x) + g2s * (a2h.x + b2h.x);
;                 r[3] = xv[3] * DN_ALPHA + g1s * (a1h.y + b1h.y) + g2s * (a2h.y + b2h.y);
;                 if constexpr (WRY) st4h((ystream_t*)Ysrc + (size_t)m * DM + (lane + 64 * j) * 4, r);
;                 v[j] = r; }
.LBB0_1432:
	s_add_u32 s10, s14, s8
	s_addc_u32 s11, s15, s9
	s_ashr_i32 s1, s0, 31
	global_load_dwordx4 v[26:29], v1, s[10:11]
	s_lshl_b64 s[10:11], s[0:1], 2
	s_add_u32 s10, s6, s10
	s_addc_u32 s11, s7, s11
	s_add_u32 s16, s14, s4
	s_addc_u32 s17, s15, s5
	global_load_dwordx2 v[40:41], v200, s[16:17] offset:80
	global_load_dwordx2 v[2:3], v1, s[10:11]
	v_lshl_add_u64 v[42:43], s[14:15], 0, v[24:25]
	global_load_dwordx2 v[26:27], v[42:43], off offset:-1024
	s_add_i32 s2, s2, s88
	s_add_i32 s0, s0, s75
	s_add_u32 s8, s8, s76
	s_addc_u32 s9, s9, s77
	s_add_u32 s4, s4, s78
	s_addc_u32 s5, s5, s79
	v_lshl_add_u64 v[24:25], v[24:25], 0, s[80:81]
	s_cmpk_gt_i32 s2, 0x3fff
	s_waitcnt vmcnt(0)
	v_mul_f32_e32 v0, 0x3c800000, v29
	v_ashrrev_i32_e32 v7, 31, v3
	v_mov_b32_e32 v6, v3
	v_ashrrev_i32_e32 v5, 31, v2
	v_mov_b32_e32 v4, v2
	v_lshlrev_b64 v[2:3], 10, v[6:7]
	v_lshl_add_u64 v[6:7], v[14:15], 0, v[2:3]
	v_lshl_add_u64 v[38:39], v[16:17], 0, v[2:3]
	v_mul_f32_e32 v2, 0x3c800000, v28
	v_cvt_f32_f16_sdwa v3, v26 dst_sel:DWORD dst_unused:UNUSED_PAD src0_sel:WORD_1
	v_cvt_f32_f16_e32 v28, v26
	v_cvt_f32_f16_sdwa v29, v27 dst_sel:DWORD dst_unused:UNUSED_PAD src0_sel:WORD_1
	v_cvt_f32_f16_e32 v26, v27
	v_lshlrev_b64 v[8:9], 10, v[4:5]
	v_sub_f32_e32 v28, v28, v40
	v_sub_f32_e32 v27, v29, v40
	v_sub_f32_e32 v26, v26, v40
	v_sub_f32_e32 v29, v3, v40
	v_pk_mul_f32 v[34:35], v[40:41], v[28:29] op_sel:[1,0]
	v_pk_mul_f32 v[36:37], v[40:41], v[26:27] op_sel:[1,0]
	global_load_dwordx4 v[26:29], v[10:11], off
	global_load_dwordx4 v[30:33], v[12:13], off
	v_lshl_add_u64 v[4:5], v[14:15], 0, v[8:9]
	v_lshl_add_u64 v[8:9], v[16:17], 0, v[8:9]
	s_waitcnt vmcnt(0)
	v_pk_fma_f32 v[28:29], v[28:29], v[36:37], v[32:33]
	global_load_dword v3, v[4:5], off
	global_load_dword v52, v[6:7], off
	global_load_dword v36, v[8:9], off
	global_load_dword v56, v[38:39], off
	v_pk_fma_f32 v[26:27], v[26:27], v[34:35], v[30:31]
	s_waitcnt vmcnt(3)
	v_cvt_pk_f32_fp8_e32 v[30:31], v3
	s_waitcnt vmcnt(2)
	v_cvt_pk_f32_fp8_e32 v[50:51], v52
	s_waitcnt vmcnt(1)
	v_cvt_pk_f32_fp8_e32 v[34:35], v36
	s_waitcnt vmcnt(0)
	v_cvt_pk_f32_fp8_e32 v[54:55], v56
	v_cvt_pk_f32_fp8_sdwa v[32:33], v3 src0_sel:WORD_1
	v_cvt_pk_f32_fp8_sdwa v[36:37], v36 src0_sel:WORD_1
	v_pk_add_f32 v[30:31], v[30:31], v[34:35]
	v_cvt_pk_f32_fp8_sdwa v[52:53], v52 src0_sel:WORD_1
	v_cvt_pk_f32_fp8_sdwa v[56:57], v56 src0_sel:WORD_1
	v_pk_mul_f32 v[30:31], v[2:3], v[30:31] op_sel_hi:[0,1]
	v_pk_fma_f32 v[26:27], v[26:27], s[36:37], v[30:31] op_sel_hi:[1,0,1]
	v_pk_add_f32 v[30:31], v[50:51], v[54:55]
	s_nop 0
	v_pk_fma_f32 v[26:27], v[0:1], v[30:31], v[26:27] op_sel_hi:[0,1,1]
	v_pk_add_f32 v[30:31], v[32:33], v[36:37]
	s_nop 0
	v_pk_mul_f32 v[30:31], v[2:3], v[30:31] op_sel_hi:[0,1]
	v_pk_fma_f32 v[28:29], v[28:29], s[36:37], v[30:31] op_sel_hi:[1,0,1]
	v_pk_add_f32 v[30:31], v[52:53], v[56:57]
	s_nop 0
	v_pk_fma_f32 v[28:29], v[0:1], v[30:31], v[28:29] op_sel_hi:[0,1,1]
	global_load_dwordx2 v[30:31], v[42:43], off offset:-512
	s_waitcnt vmcnt(0)
	v_cvt_f32_f16_sdwa v3, v30 dst_sel:DWORD dst_unused:UNUSED_PAD src0_sel:WORD_1
	v_cvt_f32_f16_e32 v32, v30
	v_cvt_f32_f16_sdwa v33, v31 dst_sel:DWORD dst_unused:UNUSED_PAD src0_sel:WORD_1
	v_cvt_f32_f16_e32 v30, v31
	v_sub_f32_e32 v32, v32, v40
	v_sub_f32_e32 v31, v33, v40
	v_sub_f32_e32 v30, v30, v40
	v_sub_f32_e32 v33, v3, v40
	v_pk_mul_f32 v[50:51], v[40:41], v[32:33] op_sel:[1,0]
	v_pk_mul_f32 v[52:53], v[40:41], v[30:31] op_sel:[1,0]
	global_load_dwordx4 v[30:33], v[10:11], off offset:1024
	global_load_dwordx4 v[34:37], v[12:13], off offset:1024
	s_waitcnt vmcnt(0)
	v_pk_fma_f32 v[32:33], v[32:33], v[52:53], v[36:37]
	global_load_dword v3, v[4:5], off offset:256
	global_load_dword v56, v[6:7], off offset:256
	global_load_dword v52, v[8:9], off offset:256
	global_load_dword v60, v[38:39], off offset:256
	v_pk_fma_f32 v[30:31], v[30:31], v[50:51], v[34:35]
	s_waitcnt vmcnt(3)
	v_cvt_pk_f32_fp8_e32 v[34:35], v3
	s_waitcnt vmcnt(2)
	v_cvt_pk_f32_fp8_e32 v[54:55], v56
	s_waitcnt vmcnt(1)
	v_cvt_pk_f32_fp8_e32 v[50:51], v52
	s_waitcnt vmcnt(0)
	v_cvt_pk_f32_fp8_e32 v[58:59], v60
	v_cvt_pk_f32_fp8_sdwa v[36:37], v3 src0_sel:WORD_1
	v_cvt_pk_f32_fp8_sdwa v[52:53], v52 src0_sel:WORD_1
	v_pk_add_f32 v[34:35], v[34:35], v[50:51]
	v_cvt_pk_f32_fp8_sdwa v[56:57], v56 src0_sel:WORD_1
	v_cvt_pk_f32_fp8_sdwa v[60:61], v60 src0_sel:WORD_1
	v_pk_mul_f32 v[34:35], v[2:3], v[34:35] op_sel_hi:[0,1]
	v_pk_fma_f32 v[30:31], v[30:31], s[36:37], v[34:35] op_sel_hi:[1,0,1]
	v_pk_add_f32 v[34:35], v[54:55], v[58:59]
	s_nop 0
	v_pk_fma_f32 v[30:31], v[0:1], v[34:35], v[30:31] op_sel_hi:[0,1,1]
	v_pk_add_f32 v[34:35], v[36:37], v[52:53]
	s_nop 0
	v_pk_mul_f32 v[34:35], v[2:3], v[34:35] op_sel_hi:[0,1]
	v_pk_fma_f32 v[32:33], v[32:33], s[36:37], v[34:35] op_sel_hi:[1,0,1]
	v_pk_add_f32 v[34:35], v[56:57], v[60:61]
	s_nop 0
	v_pk_fma_f32 v[32:33], v[0:1], v[34:35], v[32:33] op_sel_hi:[0,1,1]
	global_load_dwordx2 v[34:35], v[42:43], off
	s_waitcnt vmcnt(0)
	v_cvt_f32_f16_sdwa v3, v34 dst_sel:DWORD dst_unused:UNUSED_PAD src0_sel:WORD_1
	v_cvt_f32_f16_e32 v36, v34
	v_cvt_f32_f16_sdwa v37, v35 dst_sel:DWORD dst_unused:UNUSED_PAD src0_sel:WORD_1
	v_cvt_f32_f16_e32 v34, v35
	v_sub_f32_e32 v36, v36, v40
	v_sub_f32_e32 v35, v37, v40
	v_sub_f32_e32 v34, v34, v40
	v_sub_f32_e32 v37, v3, v40
	v_pk_mul_f32 v[54:55], v[40:41], v[36:37] op_sel:[1,0]
	v_pk_mul_f32 v[56:57], v[40:41], v[34:35] op_sel:[1,0]
	global_load_dwordx4 v[34:37], v[10:11], off offset:2048
	global_load_dwordx4 v[50:53], v[12:13], off offset:2048
	s_waitcnt vmcnt(0)
; __device__ __forceinline__ f32x4 ld4h(const ystream_t* p) { return __builtin_convertvector(*(const h16x4*)p, f32x4); }
; __device__ __forceinline__ void st4h(ystream_t* p, f32x4 v) { *(h16x4*)p = __builtin_convertvector(v, h16x4); }
;     ...
;             for (int j = 0; j < 4; ++j) { const f32x4 yv1 = ld4h(Ysrc + (size_t)m * DM + (lane + 64 * j) * 4);
;                 const f32x4 xv = (yv1 - mu1) * rs1 * *((const f32x4*)g1 + lane + 64 * j) + *((const f32x4*)b1 + lane + 64 * j);
;                 const unsigned o1 = *((const unsigned*)((const unsigned char*)oslot + (size_t)s1 * DM) + lane + 64 * j), o2 = *((const unsigned*)((const unsigned char*)oslot + (size_t)s2 * DM) + lane + 64 * j);
;                 const unsigned p1 = *((const unsigned*)((const unsigned char*)oslot2 + (size_t)s1 * DM) + lane + 64 * j), p2 = *((const unsigned*)((const unsigned char*)oslot2 + (size_t)s2 * DM) + lane + 64 * j);
;                 const f32x2 a1l = __builtin_amdgcn_cvt_pk_f32_fp8((int)o1, false), a1h = __builtin_amdgcn_cvt_pk_f32_fp8((int)o1, true), b1l = __builtin_amdgcn_cvt_pk_f32_fp8((int)p1, false), b1h = __builtin_amdgcn_cvt_pk_f32_fp8((int)p1, true);
;                 const f32x2 a2l = __builtin_amdgcn_cvt_pk_f32_fp8((int)o2, false), a2h = __builtin_amdgcn_cvt_pk_f32_fp8((int)o2, true), b2l = __builtin_amdgcn_cvt_pk_f32_fp8((int)p2, false), b2h = __builtin_amdgcn_cvt_pk_f32_fp8((int)p2, true);
;                 const float g1s = rt[2] * (1.0f / O8), g2s = rt[3] * (1.0f / O8);
;                 f32x4 r;
;                 r[0] = xv[0] * DN_ALPHA + g1s * (a1l.x + b1l.x) + g2s * (a2l.x + b2l.x);
;                 r[1] = xv[1] * DN_ALPHA + g1s * (a1l.y + b1l.y) + g2s * (a2l.y + b2l.y);
;                 r[2] = xv[2] * DN_ALPHA + g1s * (a1h.x + b1h.x) + g2s * (a2h.x + b2h.x);
;                 r[3] = xv[3] * DN_ALPHA + g1s * (a1h.y + b1h.y) + g2s * (a2h.y + b2h.y);
;                 if constexpr (WRY) st4h((ystream_t*)Ysrc + (size_t)m * DM + (lane + 64 * j) * 4, r);
;                 v[j] = r; }
;         }
;         float s = 0.f;
; #pragma unroll
;         for (int j = 0; j < 4; ++j) s += (v[j][0] + v[j][1]) + (v[j][2] + v[j][3]);
;         const float mean = wave_sum(s) * (1.f / DM); float s2 = 0.f;
	v_pk_fma_f32 v[36:37], v[36:37], v[56:57], v[52:53]
	global_load_dword v3, v[4:5], off offset:512
	global_load_dword v60, v[6:7], off offset:512
	global_load_dword v56, v[8:9], off offset:512
	global_load_dword v64, v[38:39], off offset:512
	v_pk_fma_f32 v[34:35], v[34:35], v[54:55], v[50:51]
	global_load_dwordx2 v[42:43], v[42:43], off offset:512
	s_waitcnt vmcnt(4)
	v_cvt_pk_f32_fp8_e32 v[50:51], v3
	s_waitcnt vmcnt(3)
	v_cvt_pk_f32_fp8_e32 v[58:59], v60
	s_waitcnt vmcnt(2)
	v_cvt_pk_f32_fp8_e32 v[54:55], v56
	s_waitcnt vmcnt(1)
	v_cvt_pk_f32_fp8_e32 v[62:63], v64
	v_cvt_pk_f32_fp8_sdwa v[52:53], v3 src0_sel:WORD_1
	v_cvt_pk_f32_fp8_sdwa v[56:57], v56 src0_sel:WORD_1
	v_pk_add_f32 v[50:51], v[50:51], v[54:55]
	v_cvt_pk_f32_fp8_sdwa v[60:61], v60 src0_sel:WORD_1
	v_cvt_pk_f32_fp8_sdwa v[64:65], v64 src0_sel:WORD_1
	v_pk_mul_f32 v[50:51], v[2:3], v[50:51] op_sel_hi:[0,1]
	v_pk_fma_f32 v[34:35], v[34:35], s[36:37], v[50:51] op_sel_hi:[1,0,1]
	v_pk_add_f32 v[50:51], v[58:59], v[62:63]
	s_nop 0
	v_pk_fma_f32 v[34:35], v[0:1], v[50:51], v[34:35] op_sel_hi:[0,1,1]
	v_pk_add_f32 v[50:51], v[52:53], v[56:57]
	s_nop 0
	v_pk_mul_f32 v[50:51], v[2:3], v[50:51] op_sel_hi:[0,1]
	v_pk_fma_f32 v[36:37], v[36:37], s[36:37], v[50:51] op_sel_hi:[1,0,1]
	v_pk_add_f32 v[50:51], v[60:61], v[64:65]
	s_waitcnt vmcnt(0)
	v_cvt_f32_f16_sdwa v3, v42 dst_sel:DWORD dst_unused:UNUSED_PAD src0_sel:WORD_1
	v_pk_fma_f32 v[36:37], v[0:1], v[50:51], v[36:37] op_sel_hi:[0,1,1]
	v_cvt_f32_f16_e32 v50, v42
	v_cvt_f32_f16_sdwa v51, v43 dst_sel:DWORD dst_unused:UNUSED_PAD src0_sel:WORD_1
	v_cvt_f32_f16_e32 v42, v43
	v_sub_f32_e32 v50, v50, v40
	v_sub_f32_e32 v43, v51, v40
	v_sub_f32_e32 v42, v42, v40
	v_sub_f32_e32 v51, v3, v40
	v_pk_mul_f32 v[54:55], v[40:41], v[50:51] op_sel:[1,0]
	v_pk_mul_f32 v[56:57], v[40:41], v[42:43] op_sel:[1,0]
	global_load_dwordx4 v[40:43], v[10:11], off offset:3072
	global_load_dwordx4 v[50:53], v[12:13], off offset:3072
	s_waitcnt vmcnt(0)
	v_pk_fma_f32 v[42:43], v[42:43], v[56:57], v[52:53]
	v_pk_fma_f32 v[40:41], v[40:41], v[54:55], v[50:51]
	global_load_dword v3, v[4:5], off offset:768
	global_load_dword v52, v[6:7], off offset:768
	global_load_dword v50, v[8:9], off offset:768
	global_load_dword v56, v[38:39], off offset:768
	s_waitcnt vmcnt(3)
	v_cvt_pk_f32_fp8_e32 v[4:5], v3
	s_waitcnt vmcnt(2)
	v_cvt_pk_f32_fp8_e32 v[38:39], v52
	s_waitcnt vmcnt(1)
	v_cvt_pk_f32_fp8_e32 v[8:9], v50
	s_waitcnt vmcnt(0)
	v_cvt_pk_f32_fp8_e32 v[54:55], v56
	v_cvt_pk_f32_fp8_sdwa v[6:7], v3 src0_sel:WORD_1
	v_cvt_pk_f32_fp8_sdwa v[50:51], v50 src0_sel:WORD_1
	v_pk_add_f32 v[4:5], v[4:5], v[8:9]
	v_cvt_pk_f32_fp8_sdwa v[52:53], v52 src0_sel:WORD_1
	v_cvt_pk_f32_fp8_sdwa v[56:57], v56 src0_sel:WORD_1
	v_pk_mul_f32 v[4:5], v[2:3], v[4:5] op_sel_hi:[0,1]
	v_pk_fma_f32 v[4:5], v[40:41], s[36:37], v[4:5] op_sel_hi:[1,0,1]
	v_pk_add_f32 v[8:9], v[38:39], v[54:55]
	s_nop 0
	v_pk_fma_f32 v[38:39], v[0:1], v[8:9], v[4:5] op_sel_hi:[0,1,1]
	v_pk_add_f32 v[4:5], v[6:7], v[50:51]
	v_mov_b32_e32 v6, v31
	v_pk_mul_f32 v[2:3], v[2:3], v[4:5] op_sel_hi:[0,1]
	v_pk_fma_f32 v[2:3], v[42:43], s[36:37], v[2:3] op_sel_hi:[1,0,1]
	v_pk_add_f32 v[4:5], v[52:53], v[56:57]
	v_mov_b32_e32 v7, v33
	v_pk_fma_f32 v[40:41], v[0:1], v[4:5], v[2:3] op_sel_hi:[0,1,1]
	v_mov_b32_e32 v2, v26
	v_mov_b32_e32 v3, v28
	v_mov_b32_e32 v4, v27
	v_mov_b32_e32 v5, v29
	v_pk_add_f32 v[2:3], v[2:3], v[4:5]
	v_mov_b32_e32 v4, v30
	v_mov_b32_e32 v5, v32
	v_pk_add_f32 v[4:5], v[4:5], v[6:7]
	v_add_f32_e32 v0, v2, v3
	v_pk_add_f32 v[4:5], v[4:5], v[4:5] op_sel:[0,1] op_sel_hi:[1,0]
	v_pk_add_f32 v[6:7], v[34:35], v[34:35] op_sel:[0,1] op_sel_hi:[1,0]
	v_pk_add_f32 v[8:9], v[36:37], v[36:37] op_sel:[0,1] op_sel_hi:[1,0]
	v_add_f32_e32 v2, 0, v0
	v_mov_b32_e32 v3, v38
	v_mov_b32_e32 v5, v39
	v_mov_b32_e32 v7, v40
	v_mov_b32_e32 v9, v41
	v_pk_add_f32 v[2:3], v[2:3], v[4:5]
	v_pk_add_f32 v[4:5], v[6:7], v[8:9]
	s_nop 0
	v_pk_add_f32 v[2:3], v[2:3], v[4:5]
	s_nop 0
	v_add_f32_e32 v0, v2, v3
	s_nop 1
	v_mov_b32_dpp v2, v0 quad_perm:[1,0,3,2] row_mask:0xf bank_mask:0xf
	s_nop 0
	s_waitcnt lgkmcnt(0)
	v_add_f32_e32 v0, v0, v2
	s_nop 1
	v_mov_b32_dpp v2, v0 quad_perm:[2,3,0,1] row_mask:0xf bank_mask:0xf
	s_nop 0
	s_waitcnt lgkmcnt(0)
	v_add_f32_e32 v0, v0, v2
	s_nop 1
	v_mov_b32_dpp v2, v0 row_shl:4 row_mask:0xf bank_mask:0x5
	v_mov_b32_dpp v2, v0 row_shr:4 row_mask:0xf bank_mask:0xa
	s_nop 0
	s_waitcnt lgkmcnt(0)
	v_add_f32_e32 v0, v0, v2
	s_nop 1
	v_mov_b32_dpp v2, v0 row_ror:8 row_mask:0xf bank_mask:0xf
	s_nop 0
	s_waitcnt lgkmcnt(0)
	v_add_f32_e32 v0, v0, v2
	s_nop 1
	v_mov_b32_e32 v2, v0
	v_mov_b32_e32 v43, v0
	s_nop 1
	v_permlane16_swap_b32_e32 v2, v43
	s_nop 1
	v_mov_b32_dpp v2, v43 quad_perm:[0,1,2,3] row_mask:0x5 bank_mask:0xf
	s_nop 0
	s_waitcnt lgkmcnt(0)
;     ...
;         float s = 0.f;
; #pragma unroll
;         for (int j = 0; j < 4; ++j) s += (v[j][0] + v[j][1]) + (v[j][2] + v[j][3]);
;         const float mean = wave_sum(s) * (1.f / DM); float s2 = 0.f;
; #pragma unroll
;         for (int j = 0; j < 4; ++j) { v[j] = v[j] - mean; s2 += (v[j][0] * v[j][0] + v[j][1] * v[j][1]) + (v[j][2] * v[j][2] + v[j][3] * v[j][3]); }
;         const float rstd = __builtin_amdgcn_rsqf(wave_sum(s2) * (1.f / DM) + 1e-5f);
; #pragma unroll
;         for (int j = 0; j < 4; ++j) { const f32x4 gv = *((const f32x4*)g + lane + 64 * j), bv = *((const f32x4*)b + lane + 64 * j);
;             v[j] = v[j] * rstd * gv + bv;
;             if constexpr (!NOX) *((f32x4*)(Xout + (size_t)m * DM) + lane + 64 * j) = v[j];
	v_add_f32_e32 v0, v0, v2
	s_nop 1
	v_mov_b32_e32 v2, v0
	v_mov_b32_e32 v43, v0
	s_nop 1
	v_permlane32_swap_b32_e32 v2, v43
	s_nop 1
	v_mov_b32_dpp v2, v43 quad_perm:[0,1,2,3] row_mask:0x3 bank_mask:0xf
	s_nop 0
	s_waitcnt lgkmcnt(0)
	v_add_f32_e32 v42, v0, v2
	v_fmamk_f32 v27, v42, 0xba800000, v27
	v_fmac_f32_e32 v26, 0xba800000, v42
	v_fmamk_f32 v29, v42, 0xba800000, v29
	v_fmac_f32_e32 v28, 0xba800000, v42
	v_pk_mul_f32 v[2:3], v[28:29], v[28:29]
	v_pk_mul_f32 v[4:5], v[26:27], v[26:27]
	v_fmamk_f32 v31, v42, 0xba800000, v31
	v_pk_mov_b32 v[6:7], v[4:5], v[2:3] op_sel:[1,0]
	v_mov_b32_e32 v5, v3
	v_fmac_f32_e32 v30, 0xba800000, v42
	v_fmamk_f32 v33, v42, 0xba800000, v33
	v_fmac_f32_e32 v32, 0xba800000, v42
	v_pk_add_f32 v[2:3], v[6:7], v[4:5]
	v_pk_mul_f32 v[4:5], v[32:33], v[32:33]
	v_pk_mul_f32 v[6:7], v[30:31], v[30:31]
	v_fmac_f32_e32 v34, 0xba800000, v42
	v_pk_mov_b32 v[8:9], v[6:7], v[4:5] op_sel:[1,0]
	v_mov_b32_e32 v7, v5
	v_fmamk_f32 v35, v42, 0xba800000, v35
	v_fmac_f32_e32 v36, 0xba800000, v42
	v_mul_f32_e32 v0, v34, v34
	v_pk_add_f32 v[4:5], v[8:9], v[6:7]
	v_fmamk_f32 v37, v42, 0xba800000, v37
	v_pk_fma_f32 v[6:7], v[34:35], v[34:35], v[0:1] op_sel_hi:[1,1,0]
	v_mul_f32_e32 v0, v36, v36
	v_pk_add_f32 v[2:3], v[2:3], v[2:3] op_sel_hi:[0,1]
	v_pk_add_f32 v[4:5], v[4:5], v[4:5] op_sel_hi:[0,1]
	v_pk_fma_f32 v[8:9], v[36:37], v[36:37], v[0:1] op_sel_hi:[1,1,0]
	v_fmamk_f32 v41, v42, 0xba800000, v41
	v_fmac_f32_e32 v40, 0xba800000, v42
	v_fmamk_f32 v39, v42, 0xba800000, v39
	v_fmac_f32_e32 v38, 0xba800000, v42
	v_mul_f32_e32 v6, v38, v38
	v_mul_f32_e32 v8, v39, v39
	v_mul_f32_e32 v2, v40, v40
	v_mul_f32_e32 v4, v41, v41
	v_pk_add_f32 v[6:7], v[6:7], v[8:9]
	v_pk_add_f32 v[2:3], v[2:3], v[4:5]
	s_nop 0
	v_pk_add_f32 v[2:3], v[6:7], v[2:3]
	s_nop 0
	v_add_f32_e32 v0, v2, v3
	s_nop 1
	v_mov_b32_dpp v2, v0 quad_perm:[1,0,3,2] row_mask:0xf bank_mask:0xf
	s_nop 0
	s_waitcnt lgkmcnt(0)
	v_add_f32_e32 v0, v0, v2
	s_nop 1
	v_mov_b32_dpp v2, v0 quad_perm:[2,3,0,1] row_mask:0xf bank_mask:0xf
	s_nop 0
	s_waitcnt lgkmcnt(0)
	v_add_f32_e32 v0, v0, v2
	s_nop 1
	v_mov_b32_dpp v2, v0 row_shl:4 row_mask:0xf bank_mask:0x5
	v_mov_b32_dpp v2, v0 row_shr:4 row_mask:0xf bank_mask:0xa
	s_nop 0
	s_waitcnt lgkmcnt(0)
	v_add_f32_e32 v0, v0, v2
	s_nop 1
	v_mov_b32_dpp v2, v0 row_ror:8 row_mask:0xf bank_mask:0xf
	s_nop 0
	s_waitcnt lgkmcnt(0)
	v_add_f32_e32 v0, v0, v2
	s_nop 1
	v_mov_b32_e32 v2, v0
	v_mov_b32_e32 v43, v0
	s_nop 1
	v_permlane16_swap_b32_e32 v2, v43
	s_nop 1
	v_mov_b32_dpp v2, v43 quad_perm:[0,1,2,3] row_mask:0x5 bank_mask:0xf
	s_nop 0
	s_waitcnt lgkmcnt(0)
	v_add_f32_e32 v0, v0, v2
	s_nop 1
	v_mov_b32_e32 v2, v0
	v_mov_b32_e32 v43, v0
	s_nop 1
	v_permlane32_swap_b32_e32 v2, v43
	s_nop 1
	v_mov_b32_dpp v2, v43 quad_perm:[0,1,2,3] row_mask:0x3 bank_mask:0xf
	s_nop 0
	s_waitcnt lgkmcnt(0)
	v_add_f32_e32 v0, v0, v2
	global_load_dwordx4 v[2:5], v[18:19], off
	global_load_dwordx4 v[6:9], v[20:21], off
	v_fmamk_f32 v0, v0, 0x3a800000, v199
	v_rsq_f32_e32 v0, v0
	s_nop 0
	v_pk_mul_f32 v[26:27], v[26:27], v[0:1] op_sel_hi:[1,0]
	v_pk_mul_f32 v[28:29], v[28:29], v[0:1] op_sel_hi:[1,0]
	s_waitcnt vmcnt(0)
	v_pk_fma_f32 v[2:3], v[2:3], v[26:27], v[6:7]
	v_pk_fma_f32 v[4:5], v[4:5], v[28:29], v[8:9]
	global_store_dwordx4 v[22:23], v[2:5], off
	global_load_dwordx4 v[2:5], v[18:19], off offset:1024
	s_nop 0
	global_load_dwordx4 v[6:9], v[20:21], off offset:1024
	v_pk_mul_f32 v[26:27], v[32:33], v[0:1] op_sel_hi:[1,0]
	v_pk_mul_f32 v[28:29], v[30:31], v[0:1] op_sel_hi:[1,0]
	s_waitcnt vmcnt(0)
	v_pk_fma_f32 v[4:5], v[4:5], v[26:27], v[8:9]
	v_pk_fma_f32 v[2:3], v[2:3], v[28:29], v[6:7]
	global_store_dwordx4 v[22:23], v[2:5], off offset:1024
	global_load_dwordx4 v[2:5], v[18:19], off offset:2048
	s_nop 0
	global_load_dwordx4 v[6:9], v[20:21], off offset:2048
	v_pk_mul_f32 v[26:27], v[36:37], v[0:1] op_sel_hi:[1,0]
	v_pk_mul_f32 v[28:29], v[34:35], v[0:1] op_sel_hi:[1,0]
	s_waitcnt vmcnt(0)
	v_pk_fma_f32 v[4:5], v[4:5], v[26:27], v[8:9]
	v_pk_fma_f32 v[2:3], v[2:3], v[28:29], v[6:7]
	global_store_dwordx4 v[22:23], v[2:5], off offset:2048
	global_load_dwordx4 v[2:5], v[18:19], off offset:3072
	s_nop 0
	global_load_dwordx4 v[6:9], v[20:21], off offset:3072
	v_pk_mul_f32 v[26:27], v[40:41], v[0:1] op_sel_hi:[1,0]
	v_pk_mul_f32 v[28:29], v[38:39], v[0:1] op_sel_hi:[1,0]
	s_waitcnt vmcnt(0)
	v_pk_fma_f32 v[4:5], v[4:5], v[26:27], v[8:9]
	v_pk_fma_f32 v[2:3], v[2:3], v[28:29], v[6:7]
	global_store_dwordx4 v[22:23], v[2:5], off offset:3072
	v_lshl_add_u64 v[22:23], v[22:23], 0, s[82:83]
	s_cbranch_scc0 .LBB0_1432

;     ...
;             for (int j = 0; j < 4; ++j) v[j] = ld4h(Ysrc + (size_t)m * DM + (lane + 64 * j) * 4);
;         } else {
;             const f32x4 rt = route[m]; const int s1 = slots[2 * m], s2 = slots[2 * m + 1];
;             const float mu1 = st[(size_t)m * 32 + 20], rs1 = st[(size_t)m * 32 + 21];
; #pragma unroll
;             for (int j = 0; j < 4; ++j) { const f32x4 yv1 = ld4h(Ysrc + (size_t)m * DM + (lane + 64 * j) * 4);
;                 const f32x4 xv = (yv1 - mu1) * rs1 * *((const f32x4*)g1 + lane + 64 * j) + *((const f32x4*)b1 + lane + 64 * j);
;                 const unsigned o1 = *((const unsigned*)((const unsigned char*)oslot + (size_t)s1 * DM) + lane + 64 * j), o2 = *((const unsigned*)((const unsigned char*)oslot + (size_t)s2 * DM) + lane + 64 * j);
;                 const unsigned p1 = *((const unsigned*)((const unsigned char*)oslot2 + (size_t)s1 * DM) + lane + 64 * j), p2 = *((const unsigned*)((const unsigned char*)oslot2 + (size_t)s2 * DM) + lane + 64 * j);
;                 const f32x2 a1l = __builtin_amdgcn_cvt_pk_f32_fp8((int)o1, false), a1h = __builtin_amdgcn_cvt_pk_f32_fp8((int)o1, true), b1l = __builtin_amdgcn_cvt_pk_f32_fp8((int)p1, false), b1h = __builtin_amdgcn_cvt_pk_f32_fp8((int)p1, true);
;                 const f32x2 a2l = __builtin_amdgcn_cvt_pk_f32_fp8((int)o2, false), a2h = __builtin_amdgcn_cvt_pk_f32_fp8((int)o2, true), b2l = __builtin_amdgcn_cvt_pk_f32_fp8((int)p2, false), b2h = __builtin_amdgcn_cvt_pk_f32_fp8((int)p2, true);
;                 const float g1s = rt[2] * (1.0f / O8), g2s = rt[3] * (1.0f / O8);
;                 f32x4 r;
;                 r[0] = xv[0] * DN_ALPHA + g1s * (a1l.x + b1l.x) + g2s * (a2l.x + b2l.x);
;                 r[1] = xv[1] * DN_ALPHA + g1s * (a1l.y + b1l.y) + g2s * (a2l.y + b2l.y);
;                 r[2] = xv[2] * DN_ALPHA + g1s * (a1h.x + b1h.x) + g2s * (a2h.x + b2h.x);
;                 r[3] = xv[3] * DN_ALPHA + g1s * (a1h.y + b1h.y) + g2s * (a2h.y + b2h.y);
;                 if constexpr (WRY) st4h((ystream_t*)Ysrc + (size_t)m * DM + (lane + 64 * j) * 4, r);
;                 v[j] = r; }
;         }
;         float s = 0.f;
; #pragma unroll
;         for (int j = 0; j < 4; ++j) s += (v[j][0] + v[j][1]) + (v[j][2] + v[j][3]);
;         const float mean = wave_sum(s) * (1.f / DM); float s2 = 0.f;
; #pragma unroll
.LBB0_1695:
	v_lshl_add_u64 v[10:11], s[2:3], 0, v[8:9]
	global_load_dwordx2 v[12:13], v[10:11], off offset:-1024
	global_load_dwordx2 v[18:19], v[10:11], off offset:-512
	global_load_dwordx2 v[24:25], v[10:11], off
	s_mov_b32 s4, 0xba800000
	global_load_dwordx2 v[10:11], v[10:11], off offset:512
	s_waitcnt vmcnt(0)
	v_cvt_f32_f16_e32 v14, v12
	v_cvt_f32_f16_sdwa v15, v13 dst_sel:DWORD dst_unused:UNUSED_PAD src0_sel:WORD_1
	v_cvt_f32_f16_e32 v17, v13
	v_cvt_f32_f16_sdwa v16, v12 dst_sel:DWORD dst_unused:UNUSED_PAD src0_sel:WORD_1
	v_cvt_f32_f16_e32 v20, v18
	v_cvt_f32_f16_sdwa v21, v19 dst_sel:DWORD dst_unused:UNUSED_PAD src0_sel:WORD_1
	v_cvt_f32_f16_e32 v23, v19
	v_cvt_f32_f16_sdwa v22, v18 dst_sel:DWORD dst_unused:UNUSED_PAD src0_sel:WORD_1
	v_cvt_f32_f16_e32 v0, v25
	v_cvt_f32_f16_sdwa v26, v25 dst_sel:DWORD dst_unused:UNUSED_PAD src0_sel:WORD_1
	v_cvt_f32_f16_e32 v34, v24
	v_cvt_f32_f16_sdwa v38, v24 dst_sel:DWORD dst_unused:UNUSED_PAD src0_sel:WORD_1
	v_cvt_f32_f16_sdwa v39, v10 dst_sel:DWORD dst_unused:UNUSED_PAD src0_sel:WORD_1
	v_pk_add_f32 v[14:15], v[16:17], v[14:15]
	v_cvt_f32_f16_sdwa v27, v11 dst_sel:DWORD dst_unused:UNUSED_PAD src0_sel:WORD_1
	v_cvt_f32_f16_e32 v35, v11
	v_cvt_f32_f16_e32 v37, v10
	v_add_f32_e32 v14, v14, v15
	v_add_f32_e32 v36, 0, v14
	v_pk_add_f32 v[14:15], v[22:23], v[20:21]
	v_add_f32_e32 v34, v34, v38
	v_pk_add_f32 v[14:15], v[14:15], v[14:15] op_sel:[0,1] op_sel_hi:[1,0]
	v_add_f32_e32 v26, v0, v26
	v_mov_b32_e32 v15, v39
	v_pk_add_f32 v[14:15], v[36:37], v[14:15]
	v_pk_add_f32 v[16:17], v[34:35], v[26:27]
	s_nop 0
	v_pk_add_f32 v[14:15], v[14:15], v[16:17]
	s_nop 0
	v_add_f32_e32 v0, v14, v15
	s_nop 1
	v_mov_b32_dpp v14, v0 quad_perm:[1,0,3,2] row_mask:0xf bank_mask:0xf
	s_nop 0
	s_waitcnt lgkmcnt(0)
	v_add_f32_e32 v0, v0, v14
	s_nop 1
	v_mov_b32_dpp v14, v0 quad_perm:[2,3,0,1] row_mask:0xf bank_mask:0xf
	s_nop 0
	s_waitcnt lgkmcnt(0)
	v_add_f32_e32 v0, v0, v14
	s_nop 1
	v_mov_b32_dpp v14, v0 row_shl:4 row_mask:0xf bank_mask:0x5
	v_mov_b32_dpp v14, v0 row_shr:4 row_mask:0xf bank_mask:0xa
	s_nop 0
	s_waitcnt lgkmcnt(0)
	v_add_f32_e32 v0, v0, v14
	s_nop 1
	v_mov_b32_dpp v14, v0 row_ror:8 row_mask:0xf bank_mask:0xf
	s_nop 0
	s_waitcnt lgkmcnt(0)
	v_add_f32_e32 v0, v0, v14
	s_nop 1
	v_mov_b32_e32 v14, v0
	v_mov_b32_e32 v35, v0
	s_nop 1
	v_permlane16_swap_b32_e32 v14, v35
	s_nop 1
	v_mov_b32_dpp v14, v35 quad_perm:[0,1,2,3] row_mask:0x5 bank_mask:0xf
	s_nop 0
	s_waitcnt lgkmcnt(0)
	v_add_f32_e32 v0, v0, v14
	s_nop 1
	v_mov_b32_e32 v14, v0
	v_mov_b32_e32 v35, v0
	s_nop 1
	v_permlane32_swap_b32_e32 v14, v35
	s_nop 1
	v_mov_b32_dpp v14, v35 quad_perm:[0,1,2,3] row_mask:0x3 bank_mask:0xf
	s_nop 0
	s_waitcnt lgkmcnt(0)
	v_add_f32_e32 v34, v0, v14
	v_fma_mix_f32 v27, v34, s4, v12 op_sel:[0,0,1] op_sel_hi:[0,0,1]
	v_fma_mix_f32 v26, v34, s4, v12 op_sel_hi:[0,0,1]
	v_fma_mix_f32 v37, v34, s4, v13 op_sel:[0,0,1] op_sel_hi:[0,0,1]
	v_fma_mix_f32 v36, v34, s4, v13 op_sel_hi:[0,0,1]
	v_pk_mul_f32 v[12:13], v[36:37], v[36:37]
	v_pk_mul_f32 v[14:15], v[26:27], v[26:27]
	v_fma_mix_f32 v21, v34, s4, v18 op_sel:[0,0,1] op_sel_hi:[0,0,1]
	v_pk_mov_b32 v[16:17], v[14:15], v[12:13] op_sel:[1,0]
	v_mov_b32_e32 v15, v13
	v_pk_add_f32 v[12:13], v[16:17], v[14:15]
	v_fma_mix_f32 v20, v34, s4, v18 op_sel_hi:[0,0,1]
	v_fma_mix_f32 v23, v34, s4, v19 op_sel:[0,0,1] op_sel_hi:[0,0,1]
	v_fma_mix_f32 v22, v34, s4, v19 op_sel_hi:[0,0,1]
	v_pk_add_f32 v[38:39], v[12:13], v[12:13] op_sel_hi:[0,1]
	v_pk_mul_f32 v[12:13], v[22:23], v[22:23]
	v_pk_mul_f32 v[14:15], v[20:21], v[20:21]
	v_fma_mix_f32 v18, v34, s4, v25 op_sel_hi:[0,0,1]
	v_pk_mov_b32 v[16:17], v[14:15], v[12:13] op_sel:[1,0]
	v_mov_b32_e32 v15, v13
	v_pk_add_f32 v[12:13], v[16:17], v[14:15]
	v_fma_mix_f32 v16, v34, s4, v24 op_sel_hi:[0,0,1]
	v_fma_mix_f32 v17, v34, s4, v24 op_sel:[0,0,1] op_sel_hi:[0,0,1]
	v_mul_f32_e32 v0, v16, v16
	v_fma_mix_f32 v19, v34, s4, v25 op_sel:[0,0,1] op_sel_hi:[0,0,1]
	v_pk_fma_f32 v[24:25], v[16:17], v[16:17], v[0:1] op_sel_hi:[1,1,0]
	v_mul_f32_e32 v0, v18, v18
	v_pk_add_f32 v[40:41], v[12:13], v[12:13] op_sel_hi:[0,1]
	v_pk_fma_f32 v[42:43], v[18:19], v[18:19], v[0:1] op_sel_hi:[1,1,0]
	v_fma_mix_f32 v13, v34, s4, v11 op_sel:[0,0,1] op_sel_hi:[0,0,1]
	v_fma_mix_f32 v12, v34, s4, v11 op_sel_hi:[0,0,1]
	v_fma_mix_f32 v15, v34, s4, v10 op_sel:[0,0,1] op_sel_hi:[0,0,1]
	v_fma_mix_f32 v14, v34, s4, v10 op_sel_hi:[0,0,1]
	v_mul_f32_e32 v24, v14, v14
	v_mul_f32_e32 v42, v15, v15
	v_mul_f32_e32 v38, v12, v12
	v_mul_f32_e32 v40, v13, v13
	v_pk_add_f32 v[10:11], v[24:25], v[42:43]
	v_pk_add_f32 v[24:25], v[38:39], v[40:41]
	s_nop 0
	v_pk_add_f32 v[10:11], v[10:11], v[24:25]
	s_nop 0
	v_add_f32_e32 v0, v10, v11
	s_nop 1
	v_mov_b32_dpp v10, v0 quad_perm:[1,0,3,2] row_mask:0xf bank_mask:0xf
	s_nop 0
	s_waitcnt lgkmcnt(0)
; __device__ __forceinline__ unsigned cvt_pk_bf16(float lo, float hi) { unsigned r; asm volatile("v_cvt_pk_bf16_f32 %0, %1, %2" : "=v"(r) : "v"(lo), "v"(hi)); return r; }
; __device__ __forceinline__ unsigned cvt4_fp8(float a, float b, float c, float d) { unsigned w = __builtin_amdgcn_cvt_pk_fp8_f32(a, b, 0u, false); return (unsigned)__builtin_amdgcn_cvt_pk_fp8_f32(c, d, (int)w, true); }
;     ...
;         const float mean = wave_sum(s) * (1.f / DM); float s2 = 0.f;
; #pragma unroll
;         for (int j = 0; j < 4; ++j) { v[j] = v[j] - mean; s2 += (v[j][0] * v[j][0] + v[j][1] * v[j][1]) + (v[j][2] * v[j][2] + v[j][3] * v[j][3]); }
;         const float rstd = __builtin_amdgcn_rsqf(wave_sum(s2) * (1.f / DM) + 1e-5f);
; #pragma unroll
;         for (int j = 0; j < 4; ++j) { const f32x4 gv = *((const f32x4*)g + lane + 64 * j), bv = *((const f32x4*)b + lane + 64 * j);
;             v[j] = v[j] * rstd * gv + bv;
;             if constexpr (!NOX) *((f32x4*)(Xout + (size_t)m * DM) + lane + 64 * j) = v[j];
;             if constexpr (OUT8) { *((unsigned*)((unsigned char*)XB + (size_t)m * DM) + lane + 64 * j) = cvt4_fp8(v[j][0], v[j][1], v[j][2], v[j][3]); }
;             else if (XB) { u32x2 w; w.x = cvt_pk_bf16(v[j][0], v[j][1]); w.y = cvt_pk_bf16(v[j][2], v[j][3]); *((u32x2*)(XB + (size_t)m * DM) + lane + 64 * j) = w; } }
;         if constexpr (NOX) { if (lane == 0) { st[(size_t)m * 32 + stslot] = mean; st[(size_t)m * 32 + stslot + 1] = rstd; } }
	v_add_f32_e32 v0, v0, v10
	s_nop 1
	v_mov_b32_dpp v10, v0 quad_perm:[2,3,0,1] row_mask:0xf bank_mask:0xf
	s_nop 0
	s_waitcnt lgkmcnt(0)
	v_add_f32_e32 v0, v0, v10
	s_nop 1
	v_mov_b32_dpp v10, v0 row_shl:4 row_mask:0xf bank_mask:0x5
	v_mov_b32_dpp v10, v0 row_shr:4 row_mask:0xf bank_mask:0xa
	s_nop 0
	s_waitcnt lgkmcnt(0)
	v_add_f32_e32 v0, v0, v10
	s_nop 1
	v_mov_b32_dpp v10, v0 row_ror:8 row_mask:0xf bank_mask:0xf
	s_nop 0
	s_waitcnt lgkmcnt(0)
	v_add_f32_e32 v0, v0, v10
	s_nop 1
	v_mov_b32_e32 v10, v0
	v_mov_b32_e32 v35, v0
	s_nop 1
	v_permlane16_swap_b32_e32 v10, v35
	s_nop 1
	v_mov_b32_dpp v10, v35 quad_perm:[0,1,2,3] row_mask:0x5 bank_mask:0xf
	s_nop 0
	s_waitcnt lgkmcnt(0)
	v_add_f32_e32 v0, v0, v10
	s_nop 1
	v_mov_b32_e32 v10, v0
	v_mov_b32_e32 v35, v0
	s_nop 1
	v_permlane32_swap_b32_e32 v10, v35
	s_nop 1
	v_mov_b32_dpp v10, v35 quad_perm:[0,1,2,3] row_mask:0x3 bank_mask:0xf
	s_nop 0
	s_waitcnt lgkmcnt(0)
	v_add_f32_e32 v0, v0, v10
	v_fmamk_f32 v0, v0, 0x3a800000, v199
	v_rsq_f32_e32 v0, v0
	v_lshl_add_u64 v[10:11], s[2:3], 0, v[6:7]
	v_pk_mul_f32 v[24:25], v[36:37], v[0:1] op_sel_hi:[1,0]
	global_load_dwordx4 v[36:39], v[2:3], off
	global_load_dwordx4 v[40:43], v[4:5], off
	v_pk_mul_f32 v[26:27], v[26:27], v[0:1] op_sel_hi:[1,0]
	s_waitcnt vmcnt(0)
	v_pk_fma_f32 v[24:25], v[38:39], v[24:25], v[42:43]
	v_pk_fma_f32 v[26:27], v[36:37], v[26:27], v[40:41]
	v_pk_mul_f32 v[36:37], v[22:23], v[0:1] op_sel_hi:[1,0]
	v_cvt_pk_bf16_f32 v26, v26, v27
	v_cvt_pk_bf16_f32 v27, v24, v25
	global_store_dwordx2 v[10:11], v[26:27], off offset:-1024
	v_pk_mul_f32 v[38:39], v[20:21], v[0:1] op_sel_hi:[1,0]
	global_load_dwordx4 v[20:23], v[2:3], off offset:1024
	global_load_dwordx4 v[24:27], v[4:5], off offset:1024
	s_waitcnt vmcnt(0)
	v_pk_fma_f32 v[20:21], v[20:21], v[38:39], v[24:25]
	v_pk_fma_f32 v[22:23], v[22:23], v[36:37], v[26:27]
	v_cvt_pk_bf16_f32 v20, v20, v21
	v_pk_mul_f32 v[24:25], v[18:19], v[0:1] op_sel_hi:[1,0]
	v_cvt_pk_bf16_f32 v21, v22, v23
	global_store_dwordx2 v[10:11], v[20:21], off offset:-512
	v_pk_mul_f32 v[26:27], v[16:17], v[0:1] op_sel_hi:[1,0]
	global_load_dwordx4 v[16:19], v[2:3], off offset:2048
	global_load_dwordx4 v[20:23], v[4:5], off offset:2048
	s_waitcnt vmcnt(0)
	v_pk_fma_f32 v[16:17], v[16:17], v[26:27], v[20:21]
	v_pk_fma_f32 v[18:19], v[18:19], v[24:25], v[22:23]
	v_cvt_pk_bf16_f32 v16, v16, v17
	v_pk_mul_f32 v[20:21], v[12:13], v[0:1] op_sel_hi:[1,0]
	v_cvt_pk_bf16_f32 v17, v18, v19
	global_store_dwordx2 v[10:11], v[16:17], off
	v_pk_mul_f32 v[22:23], v[14:15], v[0:1] op_sel_hi:[1,0]
	global_load_dwordx4 v[12:15], v[2:3], off offset:3072
	global_load_dwordx4 v[16:19], v[4:5], off offset:3072
	s_waitcnt vmcnt(0)
	v_pk_fma_f32 v[12:13], v[12:13], v[22:23], v[16:17]
	v_pk_fma_f32 v[14:15], v[14:15], v[20:21], v[18:19]
	v_cvt_pk_bf16_f32 v12, v12, v13
	s_nop 0
	v_cvt_pk_bf16_f32 v13, v14, v15
	global_store_dwordx2 v[10:11], v[12:13], off offset:512
	s_and_saveexec_b64 s[4:5], vcc
	s_cbranch_execz .LBB0_1694
	v_mul_f32_e32 v10, 0x3a800000, v34
	v_mov_b32_e32 v11, v0
	global_store_dwordx2 v1, v[10:11], s[0:1]
	s_branch .LBB0_1694
